# near-tile bias via extended LDS table in NSA2+MoBA loops; MoBA block-mean gating from LDS-staged means; hand-written LayerNorm phases (prefetch + DPP reductions)
# speedup vs baseline: 1.0554x; 1.0209x over previous
.LBB0_790:
	s_cmp_lt_i32 s28, 8
	s_cselect_b64 s[0:1], -1, 0
	s_cmp_gt_i32 s29, 7
	s_cselect_b64 s[2:3], -1, 0
	s_and_b64 s[0:1], s[0:1], s[2:3]
	s_andn2_b64 vcc, exec, s[0:1]
	s_cbranch_vccnz .LBB0_856
	s_mov_b64 s[8:9], exec
	v_readlane_b32 s0, v254, 4
	v_lshrrev_b32_e32 v0, 6, v200
	s_lshl_b32 s3, s30, 3
	v_readfirstlane_b32 s2, v0
	v_mbcnt_lo_u32_b32 v0, -1, 0
	v_mbcnt_hi_u32_b32 v0, -1, v0
	s_add_i32 s2, s2, s0
	s_cmp_ge_i32 s2, 0x10000
	s_cbranch_scc1 .Llna1_done
	v_lshlrev_b32_e32 v1, 3, v0
	v_lshlrev_b32_e32 v0, 4, v0
	s_add_u32 s4, s36, 0
	s_addc_u32 s5, s37, 0
	s_add_u32 s6, s38, 0
	s_addc_u32 s7, s39, 0
	global_load_dwordx4 v[80:83], v0, s[4:5] offset:0
	global_load_dwordx4 v[84:87], v0, s[4:5] offset:1024
	global_load_dwordx4 v[88:91], v0, s[4:5] offset:2048
	global_load_dwordx4 v[92:95], v0, s[4:5] offset:3072
	global_load_dwordx4 v[96:99], v0, s[6:7] offset:0
	global_load_dwordx4 v[100:103], v0, s[6:7] offset:1024
	global_load_dwordx4 v[104:107], v0, s[6:7] offset:2048
	global_load_dwordx4 v[108:111], v0, s[6:7] offset:3072
	s_add_u32 s10, s26, 0x6000000
	s_addc_u32 s11, s27, 0
	v_mov_b32_e32 v112, 0x3727c5ac
	s_add_i32 s12, s2, s3
	s_cmp_lt_i32 s12, 0x10000
	s_cselect_b32 s13, s12, s2
	s_lshl_b32 s4, s2, 12
	s_add_u32 s4, s24, s4
	s_addc_u32 s5, s25, 0
	s_lshl_b32 s6, s13, 12
	s_add_u32 s6, s24, s6
	s_addc_u32 s7, s25, 0
	global_load_dwordx4 v[48:51], v0, s[4:5] offset:0
	global_load_dwordx4 v[52:55], v0, s[4:5] offset:1024
	global_load_dwordx4 v[56:59], v0, s[4:5] offset:2048
	global_load_dwordx4 v[60:63], v0, s[4:5] offset:3072
	global_load_dwordx4 v[64:67], v0, s[6:7] offset:0
	global_load_dwordx4 v[68:71], v0, s[6:7] offset:1024
	global_load_dwordx4 v[72:75], v0, s[6:7] offset:2048
	global_load_dwordx4 v[76:79], v0, s[6:7] offset:3072
	s_waitcnt vmcnt(0)
	s_branch .Llna1_enter
.Llna1_top:
	s_waitcnt vmcnt(8)
.Llna1_enter:
	s_mov_b32 s8, s2
	s_add_i32 s9, s2, s3
	v_mov_b64_e32 v[16:17], v[48:49]
	v_mov_b64_e32 v[18:19], v[50:51]
	v_mov_b64_e32 v[20:21], v[52:53]
	v_mov_b64_e32 v[22:23], v[54:55]
	v_mov_b64_e32 v[24:25], v[56:57]
	v_mov_b64_e32 v[26:27], v[58:59]
	v_mov_b64_e32 v[28:29], v[60:61]
	v_mov_b64_e32 v[30:31], v[62:63]
	v_mov_b64_e32 v[32:33], v[64:65]
	v_mov_b64_e32 v[34:35], v[66:67]
	v_mov_b64_e32 v[36:37], v[68:69]
	v_mov_b64_e32 v[38:39], v[70:71]
	v_mov_b64_e32 v[40:41], v[72:73]
	v_mov_b64_e32 v[42:43], v[74:75]
	v_mov_b64_e32 v[44:45], v[76:77]
	v_mov_b64_e32 v[46:47], v[78:79]
	s_lshl_b32 s12, s3, 1
	s_add_i32 s2, s2, s12
	s_cmp_ge_i32 s2, 0x10000
	s_cbranch_scc1 .Llna1_nopf
	s_add_i32 s12, s2, s3
	s_cmp_lt_i32 s12, 0x10000
	s_cselect_b32 s13, s12, s2
	s_lshl_b32 s4, s2, 12
	s_add_u32 s4, s24, s4
	s_addc_u32 s5, s25, 0
	s_lshl_b32 s6, s13, 12
	s_add_u32 s6, s24, s6
	s_addc_u32 s7, s25, 0
	global_load_dwordx4 v[48:51], v0, s[4:5] offset:0
	global_load_dwordx4 v[52:55], v0, s[4:5] offset:1024
	global_load_dwordx4 v[56:59], v0, s[4:5] offset:2048
	global_load_dwordx4 v[60:63], v0, s[4:5] offset:3072
	global_load_dwordx4 v[64:67], v0, s[6:7] offset:0
	global_load_dwordx4 v[68:71], v0, s[6:7] offset:1024
	global_load_dwordx4 v[72:75], v0, s[6:7] offset:2048
	global_load_dwordx4 v[76:79], v0, s[6:7] offset:3072
.Llna1_nopf:
	v_add_f32_e32 v113, v16, v20
	v_add_f32_e32 v114, v17, v21
	v_add_f32_e32 v115, v18, v22
	v_add_f32_e32 v116, v19, v23
	v_add_f32_e32 v117, v32, v36
	v_add_f32_e32 v118, v33, v37
	v_add_f32_e32 v119, v34, v38
	v_add_f32_e32 v120, v35, v39
	v_add_f32_e32 v113, v113, v24
	v_add_f32_e32 v113, v113, v28
	v_add_f32_e32 v114, v114, v25
	v_add_f32_e32 v114, v114, v29
	v_add_f32_e32 v115, v115, v26
	v_add_f32_e32 v115, v115, v30
	v_add_f32_e32 v116, v116, v27
	v_add_f32_e32 v116, v116, v31
	v_add_f32_e32 v117, v117, v40
	v_add_f32_e32 v117, v117, v44
	v_add_f32_e32 v118, v118, v41
	v_add_f32_e32 v118, v118, v45
	v_add_f32_e32 v119, v119, v42
	v_add_f32_e32 v119, v119, v46
	v_add_f32_e32 v120, v120, v43
	v_add_f32_e32 v120, v120, v47
	v_add_f32_e32 v113, v113, v114
	v_add_f32_e32 v115, v115, v116
	v_add_f32_e32 v117, v117, v118
	v_add_f32_e32 v119, v119, v120
	v_add_f32_e32 v113, v113, v115
	v_add_f32_e32 v117, v117, v119
	s_nop 1
	v_add_f32_dpp v113, v113, v113 quad_perm:[1,0,3,2] row_mask:0xf bank_mask:0xf
	v_add_f32_dpp v117, v117, v117 quad_perm:[1,0,3,2] row_mask:0xf bank_mask:0xf
	s_nop 1
	v_add_f32_dpp v113, v113, v113 quad_perm:[2,3,0,1] row_mask:0xf bank_mask:0xf
	v_add_f32_dpp v117, v117, v117 quad_perm:[2,3,0,1] row_mask:0xf bank_mask:0xf
	s_nop 1
	v_add_f32_dpp v113, v113, v113 row_half_mirror row_mask:0xf bank_mask:0xf
	v_add_f32_dpp v117, v117, v117 row_half_mirror row_mask:0xf bank_mask:0xf
	s_nop 1
	v_add_f32_dpp v113, v113, v113 row_mirror row_mask:0xf bank_mask:0xf
	v_add_f32_dpp v117, v117, v117 row_mirror row_mask:0xf bank_mask:0xf
	s_nop 1
	v_readlane_b32 s4, v113, 0
	v_readlane_b32 s5, v113, 16
	v_readlane_b32 s6, v113, 32
	v_readlane_b32 s7, v113, 48
	v_readlane_b32 s12, v117, 0
	v_readlane_b32 s13, v117, 16
	v_readlane_b32 s0, v117, 32
	v_readlane_b32 s1, v117, 48
	s_nop 1
	v_mov_b32_e32 v113, s4
	v_mov_b32_e32 v117, s12
	v_add_f32_e32 v113, s5, v113
	v_add_f32_e32 v117, s13, v117
	v_add_f32_e32 v113, s6, v113
	v_add_f32_e32 v117, s0, v117
	v_add_f32_e32 v113, s7, v113
	v_add_f32_e32 v117, s1, v117
	v_fmamk_f32 v16, v113, 0xba800000, v16
	v_fmamk_f32 v17, v113, 0xba800000, v17
	v_fmamk_f32 v18, v113, 0xba800000, v18
	v_fmamk_f32 v19, v113, 0xba800000, v19
	v_fmamk_f32 v20, v113, 0xba800000, v20
	v_fmamk_f32 v21, v113, 0xba800000, v21
	v_fmamk_f32 v22, v113, 0xba800000, v22
	v_fmamk_f32 v23, v113, 0xba800000, v23
	v_fmamk_f32 v24, v113, 0xba800000, v24
	v_fmamk_f32 v25, v113, 0xba800000, v25
	v_fmamk_f32 v26, v113, 0xba800000, v26
	v_fmamk_f32 v27, v113, 0xba800000, v27
	v_fmamk_f32 v28, v113, 0xba800000, v28
	v_fmamk_f32 v29, v113, 0xba800000, v29
	v_fmamk_f32 v30, v113, 0xba800000, v30
	v_fmamk_f32 v31, v113, 0xba800000, v31
	v_fmamk_f32 v32, v117, 0xba800000, v32
	v_fmamk_f32 v33, v117, 0xba800000, v33
	v_fmamk_f32 v34, v117, 0xba800000, v34
	v_fmamk_f32 v35, v117, 0xba800000, v35
	v_fmamk_f32 v36, v117, 0xba800000, v36
	v_fmamk_f32 v37, v117, 0xba800000, v37
	v_fmamk_f32 v38, v117, 0xba800000, v38
	v_fmamk_f32 v39, v117, 0xba800000, v39
	v_fmamk_f32 v40, v117, 0xba800000, v40
	v_fmamk_f32 v41, v117, 0xba800000, v41
	v_fmamk_f32 v42, v117, 0xba800000, v42
	v_fmamk_f32 v43, v117, 0xba800000, v43
	v_fmamk_f32 v44, v117, 0xba800000, v44
	v_fmamk_f32 v45, v117, 0xba800000, v45
	v_fmamk_f32 v46, v117, 0xba800000, v46
	v_fmamk_f32 v47, v117, 0xba800000, v47
	v_mul_f32_e32 v113, v16, v16
	v_mul_f32_e32 v114, v17, v17
	v_mul_f32_e32 v115, v18, v18
	v_mul_f32_e32 v116, v19, v19
	v_mul_f32_e32 v117, v32, v32
	v_mul_f32_e32 v118, v33, v33
	v_mul_f32_e32 v119, v34, v34
	v_mul_f32_e32 v120, v35, v35
	v_fmac_f32_e32 v113, v20, v20
	v_fmac_f32_e32 v113, v24, v24
	v_fmac_f32_e32 v113, v28, v28
	v_fmac_f32_e32 v114, v21, v21
	v_fmac_f32_e32 v114, v25, v25
	v_fmac_f32_e32 v114, v29, v29
	v_fmac_f32_e32 v115, v22, v22
	v_fmac_f32_e32 v115, v26, v26
	v_fmac_f32_e32 v115, v30, v30
	v_fmac_f32_e32 v116, v23, v23
	v_fmac_f32_e32 v116, v27, v27
	v_fmac_f32_e32 v116, v31, v31
	v_fmac_f32_e32 v117, v36, v36
	v_fmac_f32_e32 v117, v40, v40
	v_fmac_f32_e32 v117, v44, v44
	v_fmac_f32_e32 v118, v37, v37
	v_fmac_f32_e32 v118, v41, v41
	v_fmac_f32_e32 v118, v45, v45
	v_fmac_f32_e32 v119, v38, v38
	v_fmac_f32_e32 v119, v42, v42
	v_fmac_f32_e32 v119, v46, v46
	v_fmac_f32_e32 v120, v39, v39
	v_fmac_f32_e32 v120, v43, v43
	v_fmac_f32_e32 v120, v47, v47
	v_add_f32_e32 v113, v113, v114
	v_add_f32_e32 v115, v115, v116
	v_add_f32_e32 v117, v117, v118
	v_add_f32_e32 v119, v119, v120
	v_add_f32_e32 v113, v113, v115
	v_add_f32_e32 v117, v117, v119
	s_nop 1
	v_add_f32_dpp v113, v113, v113 quad_perm:[1,0,3,2] row_mask:0xf bank_mask:0xf
	v_add_f32_dpp v117, v117, v117 quad_perm:[1,0,3,2] row_mask:0xf bank_mask:0xf
	s_nop 1
	v_add_f32_dpp v113, v113, v113 quad_perm:[2,3,0,1] row_mask:0xf bank_mask:0xf
	v_add_f32_dpp v117, v117, v117 quad_perm:[2,3,0,1] row_mask:0xf bank_mask:0xf
	s_nop 1
	v_add_f32_dpp v113, v113, v113 row_half_mirror row_mask:0xf bank_mask:0xf
	v_add_f32_dpp v117, v117, v117 row_half_mirror row_mask:0xf bank_mask:0xf
	s_nop 1
	v_add_f32_dpp v113, v113, v113 row_mirror row_mask:0xf bank_mask:0xf
	v_add_f32_dpp v117, v117, v117 row_mirror row_mask:0xf bank_mask:0xf
	s_nop 1
	v_readlane_b32 s4, v113, 0
	v_readlane_b32 s5, v113, 16
	v_readlane_b32 s6, v113, 32
	v_readlane_b32 s7, v113, 48
	v_readlane_b32 s12, v117, 0
	v_readlane_b32 s13, v117, 16
	v_readlane_b32 s0, v117, 32
	v_readlane_b32 s1, v117, 48
	s_nop 1
	v_mov_b32_e32 v113, s4
	v_mov_b32_e32 v117, s12
	v_add_f32_e32 v113, s5, v113
	v_add_f32_e32 v117, s13, v117
	v_add_f32_e32 v113, s6, v113
	v_add_f32_e32 v117, s0, v117
	v_add_f32_e32 v113, s7, v113
	v_add_f32_e32 v117, s1, v117
	v_fmamk_f32 v113, v113, 0x3a800000, v112
	v_fmamk_f32 v117, v117, 0x3a800000, v112
	v_rsq_f32_e32 v113, v113
	v_rsq_f32_e32 v117, v117
	s_nop 0
	v_mul_f32_e32 v16, v16, v113
	v_mul_f32_e32 v17, v17, v113
	v_mul_f32_e32 v18, v18, v113
	v_mul_f32_e32 v19, v19, v113
	v_mul_f32_e32 v20, v20, v113
	v_mul_f32_e32 v21, v21, v113
	v_mul_f32_e32 v22, v22, v113
	v_mul_f32_e32 v23, v23, v113
	v_mul_f32_e32 v24, v24, v113
	v_mul_f32_e32 v25, v25, v113
	v_mul_f32_e32 v26, v26, v113
	v_mul_f32_e32 v27, v27, v113
	v_mul_f32_e32 v28, v28, v113
	v_mul_f32_e32 v29, v29, v113
	v_mul_f32_e32 v30, v30, v113
	v_mul_f32_e32 v31, v31, v113
	v_fma_f32 v16, v16, v80, v96
	v_fma_f32 v17, v17, v81, v97
	v_fma_f32 v18, v18, v82, v98
	v_fma_f32 v19, v19, v83, v99
	v_fma_f32 v20, v20, v84, v100
	v_fma_f32 v21, v21, v85, v101
	v_fma_f32 v22, v22, v86, v102
	v_fma_f32 v23, v23, v87, v103
	v_fma_f32 v24, v24, v88, v104
	v_fma_f32 v25, v25, v89, v105
	v_fma_f32 v26, v26, v90, v106
	v_fma_f32 v27, v27, v91, v107
	v_fma_f32 v28, v28, v92, v108
	v_fma_f32 v29, v29, v93, v109
	v_fma_f32 v30, v30, v94, v110
	v_fma_f32 v31, v31, v95, v111
	v_mul_f32_e32 v32, v32, v117
	v_mul_f32_e32 v33, v33, v117
	v_mul_f32_e32 v34, v34, v117
	v_mul_f32_e32 v35, v35, v117
	v_mul_f32_e32 v36, v36, v117
	v_mul_f32_e32 v37, v37, v117
	v_mul_f32_e32 v38, v38, v117
	v_mul_f32_e32 v39, v39, v117
	v_mul_f32_e32 v40, v40, v117
	v_mul_f32_e32 v41, v41, v117
	v_mul_f32_e32 v42, v42, v117
	v_mul_f32_e32 v43, v43, v117
	v_mul_f32_e32 v44, v44, v117
	v_mul_f32_e32 v45, v45, v117
	v_mul_f32_e32 v46, v46, v117
	v_mul_f32_e32 v47, v47, v117
	v_fma_f32 v32, v32, v80, v96
	v_fma_f32 v33, v33, v81, v97
	v_fma_f32 v34, v34, v82, v98
	v_fma_f32 v35, v35, v83, v99
	v_fma_f32 v36, v36, v84, v100
	v_fma_f32 v37, v37, v85, v101
	v_fma_f32 v38, v38, v86, v102
	v_fma_f32 v39, v39, v87, v103
	v_fma_f32 v40, v40, v88, v104
	v_fma_f32 v41, v41, v89, v105
	v_fma_f32 v42, v42, v90, v106
	v_fma_f32 v43, v43, v91, v107
	v_fma_f32 v44, v44, v92, v108
	v_fma_f32 v45, v45, v93, v109
	v_fma_f32 v46, v46, v94, v110
	v_fma_f32 v47, v47, v95, v111
	v_cvt_pk_bf16_f32 v16, v16, v17
	v_cvt_pk_bf16_f32 v17, v18, v19
	v_cvt_pk_bf16_f32 v18, v20, v21
	v_cvt_pk_bf16_f32 v19, v22, v23
	v_cvt_pk_bf16_f32 v20, v24, v25
	v_cvt_pk_bf16_f32 v21, v26, v27
	v_cvt_pk_bf16_f32 v22, v28, v29
	v_cvt_pk_bf16_f32 v23, v30, v31
	v_cvt_pk_bf16_f32 v32, v32, v33
	v_cvt_pk_bf16_f32 v33, v34, v35
	v_cvt_pk_bf16_f32 v34, v36, v37
	v_cvt_pk_bf16_f32 v35, v38, v39
	v_cvt_pk_bf16_f32 v36, v40, v41
	v_cvt_pk_bf16_f32 v37, v42, v43
	v_cvt_pk_bf16_f32 v38, v44, v45
	v_cvt_pk_bf16_f32 v39, v46, v47
	s_lshl_b32 s4, s8, 11
	s_add_u32 s4, s10, s4
	s_addc_u32 s5, s11, 0
	global_store_dwordx2 v1, v[16:17], s[4:5] offset:0
	global_store_dwordx2 v1, v[18:19], s[4:5] offset:512
	global_store_dwordx2 v1, v[20:21], s[4:5] offset:1024
	global_store_dwordx2 v1, v[22:23], s[4:5] offset:1536
	s_cmp_ge_i32 s9, 0x10000
	s_cbranch_scc1 .Llna1_st1
	s_lshl_b32 s6, s9, 11
	s_add_u32 s6, s10, s6
	s_addc_u32 s7, s11, 0
	global_store_dwordx2 v1, v[32:33], s[6:7] offset:0
	global_store_dwordx2 v1, v[34:35], s[6:7] offset:512
	global_store_dwordx2 v1, v[36:37], s[6:7] offset:1024
	global_store_dwordx2 v1, v[38:39], s[6:7] offset:1536
.Llna1_st1:
	s_cmp_lt_i32 s2, 0x10000
	s_cbranch_scc1 .Llna1_top
.Llna1_done:
.LBB0_802:
	s_or_b64 exec, exec, s[8:9]
	s_cmp_lt_i32 s29, 9
	s_cbranch_scc1 .LBB0_856
	s_waitcnt vmcnt(0)
	s_waitcnt vmcnt(0) lgkmcnt(0)
	s_barrier
	s_mov_b64 s[2:3], exec
	v_readlane_b32 s0, v254, 1
	v_readlane_b32 s1, v254, 2
	s_and_b64 s[0:1], s[2:3], s[0:1]
	s_mov_b64 exec, s[0:1]
	s_cbranch_execz .LBB0_855
	s_add_i32 s0, 0, 0x20400
	v_mov_b32_e32 v0, s0
	s_waitcnt vmcnt(0) expcnt(0) lgkmcnt(0)
	ds_read_b32 v2, v0
	s_add_i32 s0, 0, 0x20404
	v_mov_b32_e32 v0, s0
	ds_read_b32 v0, v0
	s_waitcnt lgkmcnt(1)
	v_cmp_ne_u32_e32 vcc, 0, v2
	s_cbranch_vccnz .LBB0_819
	s_add_u32 s4, s26, 0x3300200
	s_addc_u32 s5, s27, 0
	s_add_u32 s6, s26, 0x3300400
	s_addc_u32 s7, s27, 0
	s_add_u32 s8, s26, 0x3300500
	s_addc_u32 s9, s27, 0
	s_add_u32 s10, s26, 0x3300600
	s_addc_u32 s11, s27, 0
	s_add_u32 s12, s26, 0x3300700
	s_addc_u32 s13, s27, 0
	s_add_u32 s14, s26, 0x3300800
	s_addc_u32 s15, s27, 0
	s_add_u32 s18, s26, 0x3300900
	s_addc_u32 s19, s27, 0
	s_add_u32 s20, s26, 0x3300a00
	s_addc_u32 s21, s27, 0
	s_add_u32 s34, s26, 0x3300b00
	s_addc_u32 s35, s27, 0
	s_add_u32 s44, s26, 0x3300c00
	s_addc_u32 s45, s27, 0
	s_add_u32 s50, s26, 0x3300d00
	s_addc_u32 s51, s27, 0
	s_add_u32 s52, s26, 0x3300e00
	s_addc_u32 s53, s27, 0
	s_add_u32 s54, s26, 0x3300f00
	s_addc_u32 s55, s27, 0
	s_add_u32 s58, s26, 0x3301000
	s_addc_u32 s59, s27, 0
	s_add_u32 s60, s26, 0x3301100
	s_addc_u32 s61, s27, 0
	s_add_u32 s62, s26, 0x3301200
	v_readlane_b32 s0, v254, 0
	s_addc_u32 s63, s27, 0
	s_mul_i32 s0, s31, s0
	s_add_u32 s64, s26, 0x3301300
	s_mul_i32 s0, s0, s30
	s_addc_u32 s65, s27, 0
	s_mov_b32 s1, 1
	v_mov_b32_e32 v16, 0
	s_branch .LBB0_807

.LBB0_1079:
	s_cmp_lt_i32 s28, 12
	s_cselect_b64 s[0:1], -1, 0
	s_cmp_gt_i32 s29, 11
	s_cselect_b64 s[2:3], -1, 0
	s_and_b64 s[0:1], s[0:1], s[2:3]
	s_andn2_b64 vcc, exec, s[0:1]
	s_cbranch_vccnz .LBB0_1145
	s_mov_b64 s[8:9], exec
	v_readlane_b32 s0, v254, 4
	v_lshrrev_b32_e32 v0, 6, v200
	s_lshl_b32 s3, s30, 3
	v_readfirstlane_b32 s2, v0
	v_mbcnt_lo_u32_b32 v0, -1, 0
	v_mbcnt_hi_u32_b32 v0, -1, v0
	s_add_i32 s2, s2, s0
	s_cmp_ge_i32 s2, 0x10000
	s_cbranch_scc1 .Llna2_done
	v_lshlrev_b32_e32 v1, 3, v0
	v_lshlrev_b32_e32 v0, 4, v0
	s_add_u32 s4, s40, 0
	s_addc_u32 s5, s41, 0
	s_add_u32 s6, s42, 0
	s_addc_u32 s7, s43, 0
	global_load_dwordx4 v[80:83], v0, s[4:5] offset:0
	global_load_dwordx4 v[84:87], v0, s[4:5] offset:1024
	global_load_dwordx4 v[88:91], v0, s[4:5] offset:2048
	global_load_dwordx4 v[92:95], v0, s[4:5] offset:3072
	global_load_dwordx4 v[96:99], v0, s[6:7] offset:0
	global_load_dwordx4 v[100:103], v0, s[6:7] offset:1024
	global_load_dwordx4 v[104:107], v0, s[6:7] offset:2048
	global_load_dwordx4 v[108:111], v0, s[6:7] offset:3072
	s_add_u32 s10, s26, 0x6000000
	s_addc_u32 s11, s27, 0
	v_mov_b32_e32 v112, 0x3727c5ac
	s_add_i32 s12, s2, s3
	s_cmp_lt_i32 s12, 0x10000
	s_cselect_b32 s13, s12, s2
	s_lshl_b32 s4, s2, 12
	s_add_u32 s4, s24, s4
	s_addc_u32 s5, s25, 0
	s_lshl_b32 s6, s13, 12
	s_add_u32 s6, s24, s6
	s_addc_u32 s7, s25, 0
	global_load_dwordx4 v[48:51], v0, s[4:5] offset:0
	global_load_dwordx4 v[52:55], v0, s[4:5] offset:1024
	global_load_dwordx4 v[56:59], v0, s[4:5] offset:2048
	global_load_dwordx4 v[60:63], v0, s[4:5] offset:3072
	global_load_dwordx4 v[64:67], v0, s[6:7] offset:0
	global_load_dwordx4 v[68:71], v0, s[6:7] offset:1024
	global_load_dwordx4 v[72:75], v0, s[6:7] offset:2048
	global_load_dwordx4 v[76:79], v0, s[6:7] offset:3072
	s_waitcnt vmcnt(0)
	s_branch .Llna2_enter

.Llna2_done:
.LBB0_1091:
	s_or_b64 exec, exec, s[8:9]
	s_cmp_lt_i32 s29, 13
	s_cbranch_scc1 .LBB0_1145
	s_waitcnt vmcnt(0)
	s_waitcnt vmcnt(0) lgkmcnt(0)
	s_barrier
	s_mov_b64 s[2:3], exec
	v_readlane_b32 s0, v254, 1
	v_readlane_b32 s1, v254, 2
	s_and_b64 s[0:1], s[2:3], s[0:1]
	s_mov_b64 exec, s[0:1]
	s_cbranch_execz .LBB0_1144
	s_add_i32 s0, 0, 0x20400
	v_mov_b32_e32 v0, s0
	s_waitcnt vmcnt(0) expcnt(0) lgkmcnt(0)
	ds_read_b32 v2, v0
	s_add_i32 s0, 0, 0x20404
	v_mov_b32_e32 v0, s0
	ds_read_b32 v0, v0
	s_waitcnt lgkmcnt(1)
	v_cmp_ne_u32_e32 vcc, 0, v2
	s_cbranch_vccnz .LBB0_1108
	s_add_u32 s4, s26, 0x3300200
	s_addc_u32 s5, s27, 0
	s_add_u32 s6, s26, 0x3300400
	s_addc_u32 s7, s27, 0
	s_add_u32 s8, s26, 0x3300500
	s_addc_u32 s9, s27, 0
	s_add_u32 s10, s26, 0x3300600
	s_addc_u32 s11, s27, 0
	s_add_u32 s12, s26, 0x3300700
	s_addc_u32 s13, s27, 0
	s_add_u32 s14, s26, 0x3300800
	s_addc_u32 s15, s27, 0
	s_add_u32 s18, s26, 0x3300900
	s_addc_u32 s19, s27, 0
	s_add_u32 s20, s26, 0x3300a00
	s_addc_u32 s21, s27, 0
	s_add_u32 s34, s26, 0x3300b00
	s_addc_u32 s35, s27, 0
	s_add_u32 s44, s26, 0x3300c00
	s_addc_u32 s45, s27, 0
	s_add_u32 s50, s26, 0x3300d00
	s_addc_u32 s51, s27, 0
	s_add_u32 s52, s26, 0x3300e00
	s_addc_u32 s53, s27, 0
	s_add_u32 s54, s26, 0x3300f00
	s_addc_u32 s55, s27, 0
	s_add_u32 s58, s26, 0x3301000
	s_addc_u32 s59, s27, 0
	s_add_u32 s60, s26, 0x3301100
	s_addc_u32 s61, s27, 0
	s_add_u32 s62, s26, 0x3301200
	v_readlane_b32 s0, v254, 0
	s_addc_u32 s63, s27, 0
	s_mul_i32 s0, s31, s0
	s_add_u32 s64, s26, 0x3301300
	s_mul_i32 s0, s0, s30
	s_addc_u32 s65, s27, 0
	s_mov_b32 s1, 1
	v_mov_b32_e32 v16, 0
	s_branch .LBB0_1096

.LBB0_1291:
	s_or_b64 exec, exec, s[4:5]
	v_lshrrev_b32_e32 v236, 6, v200
	v_mul_u32_u24_e32 v236, 0xc00, v236
	v_and_b32_e32 v237, 63, v200
	v_lshl_add_u32 v236, v237, 2, v236
	v_mov_b32_e32 v237, 0
	v_lshl_add_u64 v[236:237], v[236:237], 0, s[50:51]
	v_lshl_add_u64 v[236:237], v[236:237], 0, s[34:35]
	global_load_dword v238, v[236:237], off
	v_mov_b32_e32 v242, v200
	v_cmp_gt_u32_e32 vcc, 704, v242
	s_and_saveexec_b64 s[90:91], vcc
	v_cmp_lt_u32_e32 vcc, 703, v242
	v_mov_b32_e32 v252, 0xf149f2ca
	s_nop 0
	v_cndmask_b32_e64 v243, 0, 1, vcc
	v_mul_u32_u24_e32 v244, 704, v243
	v_sub_u32_e32 v244, v242, v244
	v_subrev_u32_e32 v246, 96, v244
	v_max_i32_e32 v247, 0, v246
	v_min_i32_e32 v247, 0x80, v247
	v_lshlrev_b32_e32 v247, 2, v247
	v_add_u32_e32 v247, 0x20004, v247
	ds_read_b32 v247, v247
	v_mul_u32_u24_e32 v251, 0xb00, v243
	v_lshl_add_u32 v251, v244, 2, v251
	v_add_u32_e32 v251, 0x1d000, v251
	s_waitcnt lgkmcnt(0)
	v_mul_lo_u32 v247, v247, 12
	v_add3_u32 v248, v247, v243, s94
	v_ashrrev_i32_e32 v249, 31, v248
	v_lshl_add_u64 v[248:249], v[248:249], 2, s[56:57]
	global_load_dword v250, v[248:249], off
	v_mov_b32_e32 v253, 0x1ff
	v_cmp_gt_u32_e32 vcc, v246, v253
	s_waitcnt vmcnt(0)
	v_mul_f32_e32 v250, 0x41000000, v250
	s_nop 0
	v_cndmask_b32_e32 v250, v250, v252, vcc
	ds_write_b32 v251, v250
	s_or_b64 exec, exec, s[90:91]
	v_add_u32_e32 v242, 512, v200
	v_cmp_gt_u32_e32 vcc, 704, v242
	s_and_saveexec_b64 s[90:91], vcc
	v_cmp_lt_u32_e32 vcc, 703, v242
	v_mov_b32_e32 v252, 0xf149f2ca
	s_nop 0
	v_cndmask_b32_e64 v243, 0, 1, vcc
	v_mul_u32_u24_e32 v244, 704, v243
	v_sub_u32_e32 v244, v242, v244
	v_subrev_u32_e32 v246, 96, v244
	v_max_i32_e32 v247, 0, v246
	v_min_i32_e32 v247, 0x80, v247
	v_lshlrev_b32_e32 v247, 2, v247
	v_add_u32_e32 v247, 0x20004, v247
	ds_read_b32 v247, v247
	v_mul_u32_u24_e32 v251, 0xb00, v243
	v_lshl_add_u32 v251, v244, 2, v251
	v_add_u32_e32 v251, 0x1d000, v251
	s_waitcnt lgkmcnt(0)
	v_mul_lo_u32 v247, v247, 12
	v_add3_u32 v248, v247, v243, s94
	v_ashrrev_i32_e32 v249, 31, v248
	v_lshl_add_u64 v[248:249], v[248:249], 2, s[56:57]
	global_load_dword v250, v[248:249], off
	v_mov_b32_e32 v253, 0x1ff
	v_cmp_gt_u32_e32 vcc, v246, v253
	s_waitcnt vmcnt(0)
	v_mul_f32_e32 v250, 0x41000000, v250
	s_nop 0
	v_cndmask_b32_e32 v250, v250, v252, vcc
	ds_write_b32 v251, v250
	s_or_b64 exec, exec, s[90:91]
	v_lshlrev_b32_e32 v239, 2, v200
	v_add_u32_e32 v239, 0x1e000, v239
	s_waitcnt vmcnt(0)
	ds_write_b32 v239, v238
	v_and_b32_e32 v253, 32, v200
	v_add_u32_e32 v253, 0x1e000, v253
	s_waitcnt lgkmcnt(0)
	s_barrier
	s_mov_b32 s91, 0x1d094
	s_mov_b32 s32, 0x1d114
	s_xor_b64 s[72:73], s[2:3], -1
	s_and_b64 s[0:1], s[2:3], exec
	s_cselect_b32 s97, s96, s95
	v_ashrrev_i32_e32 v80, 8, v78
	v_lshl_add_u32 v62, s97, 1, v80
	v_and_b32_e32 v81, 0xc0, v78
	v_and_b32_e32 v79, 31, v78
	v_lshl_or_b32 v83, v62, 8, v81
	v_or_b32_e32 v0, v83, v79
	v_ashrrev_i32_e32 v1, 31, v0
	v_lshl_add_u64 v[172:173], s[44:45], 0, v[0:1]
	v_bfe_u32 v82, v78, 5, 1
	v_mad_u64_u32 v[0:1], s[0:1], v172, s84, v[170:171]
	v_mad_i32_i24 v1, v173, s84, v1
	v_lshlrev_b32_e32 v168, 4, v82
	v_lshl_add_u64 v[0:1], v[0:1], 0, v[168:169]
	global_load_dwordx4 v[20:23], v[0:1], off offset:32
	global_load_dwordx4 v[28:31], v[0:1], off
	global_load_dwordx4 v[16:19], v[0:1], off offset:96
	global_load_dwordx4 v[24:27], v[0:1], off offset:64
	v_and_b32_e32 v0, 32, v78
	v_mov_b32_e32 v1, v169
	v_lshl_add_u64 v[12:13], s[34:35], 0, v[0:1]
	v_mov_b32_e32 v63, 0
	v_lshl_add_u64 v[0:1], v[12:13], 0, s[50:51]
	v_cmp_lt_i32_e32 vcc, 0, v62
	v_mov_b32_e32 v64, 0
	s_waitcnt vmcnt(3)
	v_lshlrev_b32_e32 v15, 16, v20
	s_waitcnt vmcnt(2)
	v_lshlrev_b32_e32 v14, 16, v28
	v_and_b32_e32 v45, 0xffff0000, v20
	v_and_b32_e32 v44, 0xffff0000, v28
	v_lshlrev_b32_e32 v43, 16, v21
	v_lshlrev_b32_e32 v42, 16, v29
	v_and_b32_e32 v41, 0xffff0000, v21
	v_and_b32_e32 v40, 0xffff0000, v29
	v_lshlrev_b32_e32 v39, 16, v22
	v_lshlrev_b32_e32 v38, 16, v30
	v_and_b32_e32 v37, 0xffff0000, v22
	v_and_b32_e32 v36, 0xffff0000, v30
	v_lshlrev_b32_e32 v35, 16, v23
	v_lshlrev_b32_e32 v34, 16, v31
	v_and_b32_e32 v33, 0xffff0000, v23
	v_and_b32_e32 v32, 0xffff0000, v31
	s_waitcnt vmcnt(1)
	v_lshlrev_b32_e32 v49, 16, v16
	s_waitcnt vmcnt(0)
	v_lshlrev_b32_e32 v48, 16, v24
	v_and_b32_e32 v61, 0xffff0000, v16
	v_and_b32_e32 v60, 0xffff0000, v24
	v_lshlrev_b32_e32 v59, 16, v17
	v_lshlrev_b32_e32 v58, 16, v25
	v_and_b32_e32 v57, 0xffff0000, v17
	v_and_b32_e32 v56, 0xffff0000, v25
	v_lshlrev_b32_e32 v55, 16, v18
	v_lshlrev_b32_e32 v54, 16, v26
	v_and_b32_e32 v53, 0xffff0000, v18
	v_and_b32_e32 v52, 0xffff0000, v26
	v_lshlrev_b32_e32 v51, 16, v19
	v_lshlrev_b32_e32 v50, 16, v27
	v_and_b32_e32 v47, 0xffff0000, v19
	v_and_b32_e32 v46, 0xffff0000, v27
	s_and_saveexec_b64 s[2:3], vcc
	s_cbranch_execz .LBB0_1293
	ds_read_b128 v[2:5], v253 offset:0
	ds_read_b128 v[6:9], v253 offset:64
	ds_read_b128 v[64:67], v253 offset:16
	ds_read_b128 v[68:71], v253 offset:80
	ds_read_b128 v[72:75], v253 offset:128
	ds_read_b128 v[84:87], v253 offset:192
	ds_read_b128 v[88:91], v253 offset:144
	ds_read_b128 v[92:95], v253 offset:208
	s_waitcnt lgkmcnt(7)
	v_mov_b32_e32 v10, v2
	s_waitcnt lgkmcnt(6)
	v_mov_b32_e32 v11, v6
	v_mov_b32_e32 v6, v3
	v_pk_mul_f32 v[6:7], v[6:7], v[44:45]
	v_mov_b32_e32 v2, v4
	v_mov_b32_e32 v3, v8
	v_mov_b32_e32 v8, v5
	s_waitcnt lgkmcnt(4)
	v_mov_b32_e32 v5, v68
	v_mov_b32_e32 v68, v65
	v_mov_b32_e32 v65, v70
	v_mov_b32_e32 v70, v67
	s_waitcnt lgkmcnt(2)
	v_mov_b32_e32 v67, v84
	v_mov_b32_e32 v84, v73
	v_pk_fma_f32 v[6:7], v[10:11], v[14:15], v[6:7]
	v_mov_b32_e32 v4, v64
	v_mov_b32_e32 v64, v66
	v_mov_b32_e32 v66, v72
	v_pk_mul_f32 v[84:85], v[84:85], v[60:61]
	v_pk_fma_f32 v[2:3], v[2:3], v[42:43], v[6:7]
	v_mov_b32_e32 v72, v74
	v_mov_b32_e32 v73, v86
	v_pk_fma_f32 v[10:11], v[66:67], v[48:49], v[84:85]
	v_pk_fma_f32 v[2:3], v[8:9], v[40:41], v[2:3]
	v_mov_b32_e32 v86, v75
	v_pk_fma_f32 v[6:7], v[72:73], v[58:59], v[10:11]
	v_pk_fma_f32 v[2:3], v[4:5], v[38:39], v[2:3]
	s_waitcnt lgkmcnt(1)
	v_mov_b32_e32 v74, v88
	s_waitcnt lgkmcnt(0)
	v_mov_b32_e32 v75, v92
	v_pk_fma_f32 v[6:7], v[86:87], v[56:57], v[6:7]
	v_pk_fma_f32 v[2:3], v[68:69], v[36:37], v[2:3]
	v_mov_b32_e32 v92, v89
	v_pk_fma_f32 v[4:5], v[74:75], v[54:55], v[6:7]
	v_pk_fma_f32 v[2:3], v[64:65], v[34:35], v[2:3]
	v_mov_b32_e32 v76, v90
	v_mov_b32_e32 v77, v94
	v_pk_fma_f32 v[4:5], v[92:93], v[52:53], v[4:5]
	v_pk_fma_f32 v[2:3], v[70:71], v[32:33], v[2:3]
	v_mov_b32_e32 v94, v91
	v_pk_fma_f32 v[4:5], v[76:77], v[50:51], v[4:5]
	v_add_f32_e32 v2, 0, v2
	v_add_f32_e32 v6, v2, v3
	v_pk_fma_f32 v[2:3], v[94:95], v[46:47], v[4:5]
	s_nop 0
	v_add_f32_e32 v2, v6, v2
	v_add_f32_e32 v64, v2, v3
.LBB0_1293:
	s_or_b64 exec, exec, s[2:3]
	v_and_b32_e32 v3, 64, v181
	v_xor_b32_e32 v2, 32, v181
	v_add_u32_e32 v3, 64, v3
	v_cmp_lt_i32_e64 s[2:3], v2, v3
	s_nop 1
	v_cndmask_b32_e64 v2, v181, v2, s[2:3]
	v_lshlrev_b32_e32 v204, 2, v2
	ds_bpermute_b32 v65, v204, v64
	v_cmp_lt_i32_e64 s[2:3], 1, v62
	v_lshl_add_u64 v[2:3], v[12:13], 0, s[52:53]
	s_and_saveexec_b64 s[4:5], s[2:3]
	s_cbranch_execz .LBB0_1295
	ds_read_b128 v[4:7], v253 offset:256
	ds_read_b128 v[8:11], v253 offset:320
	ds_read_b128 v[66:69], v253 offset:272
	ds_read_b128 v[70:73], v253 offset:336
	ds_read_b128 v[74:77], v253 offset:384
	ds_read_b128 v[84:87], v253 offset:448
	ds_read_b128 v[88:91], v253 offset:400
	ds_read_b128 v[92:95], v253 offset:464
	s_waitcnt lgkmcnt(7)
	v_mov_b32_e32 v96, v4
	s_waitcnt lgkmcnt(6)
	v_mov_b32_e32 v97, v8
	v_mov_b32_e32 v8, v5
	v_pk_mul_f32 v[8:9], v[8:9], v[44:45]
	v_mov_b32_e32 v4, v6
	v_mov_b32_e32 v5, v10
	v_mov_b32_e32 v10, v7
	s_waitcnt lgkmcnt(4)
	v_mov_b32_e32 v7, v70
	v_mov_b32_e32 v70, v67
	v_mov_b32_e32 v67, v72
	v_mov_b32_e32 v72, v69
	s_waitcnt lgkmcnt(2)
	v_mov_b32_e32 v69, v84
	v_mov_b32_e32 v84, v75
	v_pk_fma_f32 v[8:9], v[96:97], v[14:15], v[8:9]
	v_mov_b32_e32 v6, v66
	v_mov_b32_e32 v66, v68
	v_mov_b32_e32 v68, v74
	v_pk_mul_f32 v[84:85], v[84:85], v[60:61]
	v_pk_fma_f32 v[4:5], v[4:5], v[42:43], v[8:9]
	v_mov_b32_e32 v74, v76
	v_mov_b32_e32 v75, v86
	v_pk_fma_f32 v[68:69], v[68:69], v[48:49], v[84:85]
	v_pk_fma_f32 v[4:5], v[10:11], v[40:41], v[4:5]
	v_mov_b32_e32 v86, v77
	v_pk_fma_f32 v[8:9], v[74:75], v[58:59], v[68:69]
	v_pk_fma_f32 v[4:5], v[6:7], v[38:39], v[4:5]
	s_waitcnt lgkmcnt(1)
	v_mov_b32_e32 v76, v88
	s_waitcnt lgkmcnt(0)
	v_mov_b32_e32 v77, v92
	v_pk_fma_f32 v[8:9], v[86:87], v[56:57], v[8:9]
	v_pk_fma_f32 v[4:5], v[70:71], v[36:37], v[4:5]
	v_mov_b32_e32 v92, v89
	v_pk_fma_f32 v[6:7], v[76:77], v[54:55], v[8:9]
	v_pk_fma_f32 v[4:5], v[66:67], v[34:35], v[4:5]
	v_mov_b32_e32 v88, v90
	v_mov_b32_e32 v89, v94
	v_pk_fma_f32 v[6:7], v[92:93], v[52:53], v[6:7]
	v_pk_fma_f32 v[4:5], v[72:73], v[32:33], v[4:5]
	v_mov_b32_e32 v94, v91
	v_pk_fma_f32 v[6:7], v[88:89], v[50:51], v[6:7]
	v_add_f32_e32 v4, 0, v4
	v_add_f32_e32 v8, v4, v5
	v_pk_fma_f32 v[4:5], v[94:95], v[46:47], v[6:7]
	s_nop 0
	v_add_f32_e32 v4, v8, v4
	v_add_f32_e32 v63, v4, v5
.LBB0_1295:
	s_or_b64 exec, exec, s[4:5]
	ds_bpermute_b32 v66, v204, v63
	v_cmp_lt_i32_e64 s[4:5], 2, v62
	v_mov_b32_e32 v67, 0
	v_lshl_add_u64 v[4:5], v[12:13], 0, s[54:55]
	v_mov_b32_e32 v68, 0
	s_and_saveexec_b64 s[6:7], s[4:5]
	s_cbranch_execz .LBB0_1297
	ds_read_b128 v[6:9], v253 offset:512
	ds_read_b128 v[68:71], v253 offset:576
	ds_read_b128 v[72:75], v253 offset:528
	ds_read_b128 v[84:87], v253 offset:592
	ds_read_b128 v[88:91], v253 offset:640
	ds_read_b128 v[92:95], v253 offset:704
	ds_read_b128 v[96:99], v253 offset:656
	ds_read_b128 v[100:103], v253 offset:720
	s_waitcnt lgkmcnt(7)
	v_mov_b32_e32 v10, v6
	s_waitcnt lgkmcnt(6)
	v_mov_b32_e32 v11, v68
	v_mov_b32_e32 v68, v7
	v_pk_mul_f32 v[68:69], v[68:69], v[44:45]
	v_mov_b32_e32 v6, v8
	v_mov_b32_e32 v7, v70
	v_mov_b32_e32 v70, v9
	s_waitcnt lgkmcnt(4)
	v_mov_b32_e32 v9, v84
	v_mov_b32_e32 v84, v73
	v_mov_b32_e32 v73, v86
	v_mov_b32_e32 v86, v75
	s_waitcnt lgkmcnt(2)
	v_mov_b32_e32 v75, v92
	v_mov_b32_e32 v92, v89
	v_pk_fma_f32 v[10:11], v[10:11], v[14:15], v[68:69]
	v_mov_b32_e32 v8, v72
	v_mov_b32_e32 v72, v74
	v_mov_b32_e32 v74, v88
	v_pk_mul_f32 v[92:93], v[92:93], v[60:61]
	v_pk_fma_f32 v[6:7], v[6:7], v[42:43], v[10:11]
	v_mov_b32_e32 v76, v90
	v_mov_b32_e32 v77, v94
	v_pk_fma_f32 v[68:69], v[74:75], v[48:49], v[92:93]
	v_pk_fma_f32 v[6:7], v[70:71], v[40:41], v[6:7]
	v_mov_b32_e32 v94, v91
	v_pk_fma_f32 v[10:11], v[76:77], v[58:59], v[68:69]
	v_pk_fma_f32 v[6:7], v[8:9], v[38:39], v[6:7]
	s_waitcnt lgkmcnt(1)
	v_mov_b32_e32 v88, v96
	s_waitcnt lgkmcnt(0)
	v_mov_b32_e32 v89, v100
	v_pk_fma_f32 v[10:11], v[94:95], v[56:57], v[10:11]
	v_pk_fma_f32 v[6:7], v[84:85], v[36:37], v[6:7]
	v_mov_b32_e32 v100, v97
	v_pk_fma_f32 v[8:9], v[88:89], v[54:55], v[10:11]
	v_pk_fma_f32 v[6:7], v[72:73], v[34:35], v[6:7]
	v_mov_b32_e32 v90, v98
	v_mov_b32_e32 v91, v102
	v_pk_fma_f32 v[8:9], v[100:101], v[52:53], v[8:9]
	v_pk_fma_f32 v[6:7], v[86:87], v[32:33], v[6:7]
	v_mov_b32_e32 v102, v99
	v_pk_fma_f32 v[8:9], v[90:91], v[50:51], v[8:9]
	v_add_f32_e32 v6, 0, v6
	v_add_f32_e32 v10, v6, v7
	v_pk_fma_f32 v[6:7], v[102:103], v[46:47], v[8:9]
	s_nop 0
	v_add_f32_e32 v6, v10, v6
	v_add_f32_e32 v68, v6, v7
.LBB0_1297:
	s_or_b64 exec, exec, s[6:7]
	ds_bpermute_b32 v69, v204, v68
	v_cmp_lt_i32_e64 s[6:7], 3, v62
	v_lshl_add_u64 v[6:7], v[12:13], 0, s[58:59]
	s_and_saveexec_b64 s[8:9], s[6:7]
	s_cbranch_execz .LBB0_1299
	ds_read_b128 v[8:11], v253 offset:768
	ds_read_b128 v[70:73], v253 offset:832
	ds_read_b128 v[74:77], v253 offset:784
	ds_read_b128 v[84:87], v253 offset:848
	ds_read_b128 v[88:91], v253 offset:896
	ds_read_b128 v[92:95], v253 offset:960
	ds_read_b128 v[96:99], v253 offset:912
	ds_read_b128 v[100:103], v253 offset:976
	s_waitcnt lgkmcnt(7)
	v_mov_b32_e32 v104, v8
	s_waitcnt lgkmcnt(6)
	v_mov_b32_e32 v105, v70
	v_mov_b32_e32 v70, v9
	v_pk_mul_f32 v[70:71], v[70:71], v[44:45]
	v_mov_b32_e32 v8, v10
	v_mov_b32_e32 v9, v72
	v_mov_b32_e32 v72, v11
	s_waitcnt lgkmcnt(4)
	v_mov_b32_e32 v11, v84
	v_mov_b32_e32 v84, v75
	v_mov_b32_e32 v75, v86
	v_mov_b32_e32 v86, v77
	s_waitcnt lgkmcnt(2)
	v_mov_b32_e32 v77, v92
	v_mov_b32_e32 v92, v89
	v_pk_fma_f32 v[70:71], v[104:105], v[14:15], v[70:71]
	v_mov_b32_e32 v10, v74
	v_mov_b32_e32 v74, v76
	v_mov_b32_e32 v76, v88
	v_pk_mul_f32 v[92:93], v[92:93], v[60:61]
	v_pk_fma_f32 v[8:9], v[8:9], v[42:43], v[70:71]
	v_mov_b32_e32 v88, v90
	v_mov_b32_e32 v89, v94
	v_pk_fma_f32 v[76:77], v[76:77], v[48:49], v[92:93]
	v_pk_fma_f32 v[8:9], v[72:73], v[40:41], v[8:9]
	v_mov_b32_e32 v94, v91
	v_pk_fma_f32 v[70:71], v[88:89], v[58:59], v[76:77]
	v_pk_fma_f32 v[8:9], v[10:11], v[38:39], v[8:9]
	s_waitcnt lgkmcnt(1)
	v_mov_b32_e32 v90, v96
	s_waitcnt lgkmcnt(0)
	v_mov_b32_e32 v91, v100
	v_pk_fma_f32 v[70:71], v[94:95], v[56:57], v[70:71]
	v_pk_fma_f32 v[8:9], v[84:85], v[36:37], v[8:9]
	v_mov_b32_e32 v100, v97
	v_pk_fma_f32 v[10:11], v[90:91], v[54:55], v[70:71]
	v_pk_fma_f32 v[8:9], v[74:75], v[34:35], v[8:9]
	v_mov_b32_e32 v96, v98
	v_mov_b32_e32 v97, v102
	v_pk_fma_f32 v[10:11], v[100:101], v[52:53], v[10:11]
	v_pk_fma_f32 v[8:9], v[86:87], v[32:33], v[8:9]
	v_mov_b32_e32 v102, v99
	v_pk_fma_f32 v[10:11], v[96:97], v[50:51], v[10:11]
	v_add_f32_e32 v8, 0, v8
	v_add_f32_e32 v67, v8, v9
	v_pk_fma_f32 v[8:9], v[102:103], v[46:47], v[10:11]
	s_nop 0
	v_add_f32_e32 v8, v67, v8
	v_add_f32_e32 v67, v8, v9
.LBB0_1299:
	s_or_b64 exec, exec, s[8:9]
	ds_bpermute_b32 v70, v204, v67
	v_cmp_lt_i32_e64 s[8:9], 4, v62
	v_mov_b32_e32 v71, 0
	v_lshl_add_u64 v[8:9], v[12:13], 0, s[60:61]
	v_mov_b32_e32 v72, 0
	s_and_saveexec_b64 s[10:11], s[8:9]
	s_cbranch_execz .LBB0_1301
	ds_read_b128 v[72:75], v253 offset:1024
	ds_read_b128 v[84:87], v253 offset:1088
	ds_read_b128 v[88:91], v253 offset:1040
	ds_read_b128 v[92:95], v253 offset:1104
	ds_read_b128 v[96:99], v253 offset:1152
	ds_read_b128 v[100:103], v253 offset:1216
	ds_read_b128 v[104:107], v253 offset:1168
	ds_read_b128 v[108:111], v253 offset:1232
	s_waitcnt lgkmcnt(7)
	v_mov_b32_e32 v10, v72
	s_waitcnt lgkmcnt(6)
	v_mov_b32_e32 v11, v84
	v_mov_b32_e32 v84, v73
	v_pk_mul_f32 v[84:85], v[84:85], v[44:45]
	v_mov_b32_e32 v72, v74
	v_mov_b32_e32 v73, v86
	v_mov_b32_e32 v86, v75
	s_waitcnt lgkmcnt(4)
	v_mov_b32_e32 v75, v92
	v_mov_b32_e32 v92, v89
	s_waitcnt lgkmcnt(2)
	v_mov_b32_e32 v89, v100
	v_mov_b32_e32 v100, v97
	v_pk_fma_f32 v[10:11], v[10:11], v[14:15], v[84:85]
	v_mov_b32_e32 v74, v88
	v_mov_b32_e32 v88, v96
	v_pk_mul_f32 v[100:101], v[100:101], v[60:61]
	v_pk_fma_f32 v[10:11], v[72:73], v[42:43], v[10:11]
	v_mov_b32_e32 v76, v90
	v_mov_b32_e32 v77, v94
	v_mov_b32_e32 v94, v91
	v_mov_b32_e32 v90, v98
	v_mov_b32_e32 v91, v102
	v_pk_fma_f32 v[84:85], v[88:89], v[48:49], v[100:101]
	v_pk_fma_f32 v[10:11], v[86:87], v[40:41], v[10:11]
	v_mov_b32_e32 v102, v99
	v_pk_fma_f32 v[72:73], v[90:91], v[58:59], v[84:85]
	v_pk_fma_f32 v[10:11], v[74:75], v[38:39], v[10:11]
	s_waitcnt lgkmcnt(1)
	v_mov_b32_e32 v96, v104
	s_waitcnt lgkmcnt(0)
	v_mov_b32_e32 v97, v108
	v_pk_fma_f32 v[72:73], v[102:103], v[56:57], v[72:73]
	v_pk_fma_f32 v[10:11], v[92:93], v[36:37], v[10:11]
	v_mov_b32_e32 v108, v105
	v_pk_fma_f32 v[72:73], v[96:97], v[54:55], v[72:73]
	v_pk_fma_f32 v[10:11], v[76:77], v[34:35], v[10:11]
	v_mov_b32_e32 v98, v106
	v_mov_b32_e32 v99, v110
	v_pk_fma_f32 v[72:73], v[108:109], v[52:53], v[72:73]
	v_pk_fma_f32 v[10:11], v[94:95], v[32:33], v[10:11]
	v_mov_b32_e32 v110, v107
	v_pk_fma_f32 v[72:73], v[98:99], v[50:51], v[72:73]
	v_add_f32_e32 v10, 0, v10
	v_add_f32_e32 v74, v10, v11
	v_pk_fma_f32 v[10:11], v[110:111], v[46:47], v[72:73]
	s_nop 0
	v_add_f32_e32 v10, v74, v10
	v_add_f32_e32 v72, v10, v11
.LBB0_1301:
	s_or_b64 exec, exec, s[10:11]
	ds_bpermute_b32 v73, v204, v72
	v_cmp_lt_i32_e64 s[10:11], 5, v62
	v_lshl_add_u64 v[10:11], v[12:13], 0, s[62:63]
	s_and_saveexec_b64 s[12:13], s[10:11]
	s_cbranch_execz .LBB0_1303
	ds_read_b128 v[74:77], v253 offset:1280
	ds_read_b128 v[84:87], v253 offset:1344
	ds_read_b128 v[88:91], v253 offset:1296
	ds_read_b128 v[92:95], v253 offset:1360
	ds_read_b128 v[96:99], v253 offset:1408
	ds_read_b128 v[100:103], v253 offset:1472
	ds_read_b128 v[104:107], v253 offset:1424
	ds_read_b128 v[108:111], v253 offset:1488
	s_waitcnt lgkmcnt(7)
	v_mov_b32_e32 v112, v74
	s_waitcnt lgkmcnt(6)
	v_mov_b32_e32 v113, v84
	v_mov_b32_e32 v84, v75
	v_pk_mul_f32 v[84:85], v[84:85], v[44:45]
	v_mov_b32_e32 v74, v76
	v_mov_b32_e32 v75, v86
	v_mov_b32_e32 v86, v77
	s_waitcnt lgkmcnt(4)
	v_mov_b32_e32 v77, v92
	v_mov_b32_e32 v92, v89
	v_mov_b32_e32 v89, v94
	v_mov_b32_e32 v94, v91
	s_waitcnt lgkmcnt(2)
	v_mov_b32_e32 v91, v100
	v_mov_b32_e32 v100, v97
	v_pk_fma_f32 v[84:85], v[112:113], v[14:15], v[84:85]
	v_mov_b32_e32 v76, v88
	v_mov_b32_e32 v88, v90
	v_mov_b32_e32 v90, v96
	v_pk_mul_f32 v[100:101], v[100:101], v[60:61]
	v_pk_fma_f32 v[74:75], v[74:75], v[42:43], v[84:85]
	v_mov_b32_e32 v96, v98
	v_mov_b32_e32 v97, v102
	v_pk_fma_f32 v[90:91], v[90:91], v[48:49], v[100:101]
	v_pk_fma_f32 v[74:75], v[86:87], v[40:41], v[74:75]
	v_mov_b32_e32 v102, v99
	v_pk_fma_f32 v[84:85], v[96:97], v[58:59], v[90:91]
	v_pk_fma_f32 v[74:75], v[76:77], v[38:39], v[74:75]
	s_waitcnt lgkmcnt(1)
	v_mov_b32_e32 v98, v104
	s_waitcnt lgkmcnt(0)
	v_mov_b32_e32 v99, v108
	v_pk_fma_f32 v[84:85], v[102:103], v[56:57], v[84:85]
	v_pk_fma_f32 v[74:75], v[92:93], v[36:37], v[74:75]
	v_mov_b32_e32 v108, v105
	v_pk_fma_f32 v[76:77], v[98:99], v[54:55], v[84:85]
	v_pk_fma_f32 v[74:75], v[88:89], v[34:35], v[74:75]
	v_mov_b32_e32 v104, v106
	v_mov_b32_e32 v105, v110
	v_pk_fma_f32 v[76:77], v[108:109], v[52:53], v[76:77]
	v_pk_fma_f32 v[74:75], v[94:95], v[32:33], v[74:75]
	v_mov_b32_e32 v110, v107
	v_pk_fma_f32 v[76:77], v[104:105], v[50:51], v[76:77]
	v_add_f32_e32 v71, 0, v74
	v_add_f32_e32 v71, v71, v75
	v_pk_fma_f32 v[74:75], v[110:111], v[46:47], v[76:77]
	s_nop 0
	v_add_f32_e32 v71, v71, v74
	v_add_f32_e32 v71, v71, v75
.LBB0_1303:
	s_or_b64 exec, exec, s[12:13]
	ds_bpermute_b32 v74, v204, v71
	v_cmp_lt_i32_e64 s[12:13], 6, v62
	v_mov_b32_e32 v75, 0
	v_lshl_add_u64 v[12:13], v[12:13], 0, s[64:65]
	s_and_saveexec_b64 s[14:15], s[12:13]
	s_cbranch_execz .LBB0_1305
	ds_read_b128 v[84:87], v253 offset:1536
	ds_read_b128 v[88:91], v253 offset:1600
	ds_read_b128 v[92:95], v253 offset:1552
	ds_read_b128 v[96:99], v253 offset:1616
	ds_read_b128 v[100:103], v253 offset:1664
	ds_read_b128 v[104:107], v253 offset:1728
	ds_read_b128 v[108:111], v253 offset:1680
	ds_read_b128 v[112:115], v253 offset:1744
	s_waitcnt lgkmcnt(7)
	v_mov_b32_e32 v76, v84
	s_waitcnt lgkmcnt(6)
	v_mov_b32_e32 v77, v88
	v_mov_b32_e32 v88, v85
	v_pk_mul_f32 v[44:45], v[88:89], v[44:45]
	v_mov_b32_e32 v84, v86
	v_mov_b32_e32 v85, v90
	v_mov_b32_e32 v90, v87
	s_waitcnt lgkmcnt(4)
	v_mov_b32_e32 v87, v96
	v_mov_b32_e32 v96, v93
	v_mov_b32_e32 v93, v98
	v_mov_b32_e32 v98, v95
	s_waitcnt lgkmcnt(2)
	v_mov_b32_e32 v95, v104
	v_mov_b32_e32 v104, v101
	v_pk_fma_f32 v[14:15], v[76:77], v[14:15], v[44:45]
	v_mov_b32_e32 v86, v92
	v_mov_b32_e32 v92, v94
	v_mov_b32_e32 v94, v100
	v_pk_mul_f32 v[60:61], v[104:105], v[60:61]
	v_pk_fma_f32 v[14:15], v[84:85], v[42:43], v[14:15]
	v_mov_b32_e32 v100, v102
	v_mov_b32_e32 v101, v106
	v_pk_fma_f32 v[44:45], v[94:95], v[48:49], v[60:61]
	v_pk_fma_f32 v[14:15], v[90:91], v[40:41], v[14:15]
	v_mov_b32_e32 v106, v103
	v_pk_fma_f32 v[42:43], v[100:101], v[58:59], v[44:45]
	v_pk_fma_f32 v[14:15], v[86:87], v[38:39], v[14:15]
	s_waitcnt lgkmcnt(1)
	v_mov_b32_e32 v102, v108
	s_waitcnt lgkmcnt(0)
	v_mov_b32_e32 v103, v112
	v_pk_fma_f32 v[40:41], v[106:107], v[56:57], v[42:43]
	v_pk_fma_f32 v[14:15], v[96:97], v[36:37], v[14:15]
	v_mov_b32_e32 v112, v109
	v_pk_fma_f32 v[38:39], v[102:103], v[54:55], v[40:41]
	v_pk_fma_f32 v[14:15], v[92:93], v[34:35], v[14:15]
	v_mov_b32_e32 v108, v110
	v_mov_b32_e32 v109, v114
	v_pk_fma_f32 v[36:37], v[112:113], v[52:53], v[38:39]
	v_pk_fma_f32 v[14:15], v[98:99], v[32:33], v[14:15]
	v_mov_b32_e32 v114, v111
	v_pk_fma_f32 v[34:35], v[108:109], v[50:51], v[36:37]
	v_add_f32_e32 v14, 0, v14
	v_add_f32_e32 v32, v14, v15
	v_pk_fma_f32 v[14:15], v[114:115], v[46:47], v[34:35]
	s_nop 0
	v_add_f32_e32 v14, v32, v14
	v_add_f32_e32 v75, v14, v15

.LBB0_1306:
	v_and_b32_e32 v38, 1, v37
	v_cmp_eq_u32_e64 s[18:19], 0, v38
	s_or_b64 s[18:19], s[18:19], s[14:15]
	v_and_b32_e32 v40, 2, v37
	v_cndmask_b32_e64 v39, v35, v199, s[18:19]
	v_cndmask_b32_e64 v38, 0, -1, s[18:19]
	v_cmp_ne_u32_e64 s[18:19], 0, v40
	v_cmp_gt_f32_e64 s[20:21], v34, v39
	s_and_b64 s[18:19], s[18:19], s[20:21]
	v_cndmask_b32_e64 v39, v39, v34, s[18:19]
	v_and_b32_e32 v40, 4, v37
	v_cndmask_b32_e64 v38, v38, 1, s[18:19]
	v_cmp_ne_u32_e64 s[18:19], 0, v40
	v_cmp_gt_f32_e64 s[20:21], v33, v39
	s_and_b64 s[18:19], s[18:19], s[20:21]
	v_cndmask_b32_e64 v39, v39, v33, s[18:19]
	v_and_b32_e32 v40, 8, v37
	v_cndmask_b32_e64 v38, v38, 2, s[18:19]
	v_cmp_ne_u32_e64 s[18:19], 0, v40
	v_cmp_gt_f32_e64 s[20:21], v32, v39
	s_and_b64 s[18:19], s[18:19], s[20:21]
	v_cndmask_b32_e64 v39, v39, v32, s[18:19]
	v_and_b32_e32 v40, 16, v37
	v_cndmask_b32_e64 v38, v38, 3, s[18:19]
	v_cmp_ne_u32_e64 s[18:19], 0, v40
	v_cmp_gt_f32_e64 s[20:21], v15, v39
	s_and_b64 s[18:19], s[18:19], s[20:21]
	v_cndmask_b32_e64 v39, v39, v15, s[18:19]
	v_and_b32_e32 v40, 32, v37
	v_cndmask_b32_e64 v38, v38, 4, s[18:19]
	v_cmp_ne_u32_e64 s[18:19], 0, v40
	v_cmp_gt_f32_e64 s[20:21], v14, v39
	s_and_b64 s[18:19], s[18:19], s[20:21]
	v_cndmask_b32_e64 v39, v39, v14, s[18:19]
	v_and_b32_e32 v40, 64, v37
	v_cndmask_b32_e64 v38, v38, 5, s[18:19]
	v_cmp_ne_u32_e64 s[18:19], 0, v40
	v_cmp_gt_f32_e64 s[20:21], v36, v39
	s_and_b64 s[18:19], s[18:19], s[20:21]
	v_cndmask_b32_e64 v38, v38, 6, s[18:19]
	v_lshlrev_b32_e64 v39, v38, 1
	v_cmp_lt_i32_e64 s[18:19], -1, v38
	v_not_b32_e32 v40, v39
	s_add_i32 s0, s0, -1
	v_cndmask_b32_e64 v38, 0, v39, s[18:19]
	v_or_b32_e32 v205, v38, v205
	v_cndmask_b32_e64 v38, -1, v40, s[18:19]
	s_cmp_lg_u32 s0, 0
	v_and_b32_e32 v37, v38, v37
	s_cbranch_scc1 .LBB0_1306
	v_or_b32_e32 v176, 32, v172
	v_mov_b64_e32 v[14:15], s[66:67]
	v_mad_u64_u32 v[14:15], s[0:1], v176, s84, v[14:15]
	v_mad_i32_i24 v15, v173, s84, v15
	v_lshlrev_b32_e32 v32, 1, v174
	v_mov_b32_e32 v33, v169
	v_lshl_add_u64 v[14:15], v[14:15], 0, v[32:33]
	global_load_dwordx4 v[52:55], v[14:15], off offset:32
	global_load_dwordx4 v[60:63], v[14:15], off
	global_load_dwordx4 v[48:51], v[14:15], off offset:96
	global_load_dwordx4 v[56:59], v[14:15], off offset:64
	v_mov_b32_e32 v86, 0
	v_mov_b32_e32 v87, 0
	s_waitcnt vmcnt(3)
	v_lshlrev_b32_e32 v15, 16, v52
	s_waitcnt vmcnt(2)
	v_lshlrev_b32_e32 v14, 16, v60
	v_and_b32_e32 v45, 0xffff0000, v52
	v_and_b32_e32 v44, 0xffff0000, v60
	v_lshlrev_b32_e32 v43, 16, v53
	v_lshlrev_b32_e32 v42, 16, v61
	v_and_b32_e32 v41, 0xffff0000, v53
	v_and_b32_e32 v40, 0xffff0000, v61
	v_lshlrev_b32_e32 v39, 16, v54
	v_lshlrev_b32_e32 v38, 16, v62
	v_and_b32_e32 v37, 0xffff0000, v54
	v_and_b32_e32 v36, 0xffff0000, v62
	v_lshlrev_b32_e32 v35, 16, v55
	v_lshlrev_b32_e32 v34, 16, v63
	v_and_b32_e32 v33, 0xffff0000, v55
	v_and_b32_e32 v32, 0xffff0000, v63
	s_waitcnt vmcnt(1)
	v_lshlrev_b32_e32 v65, 16, v48
	s_waitcnt vmcnt(0)
	v_lshlrev_b32_e32 v64, 16, v56
	v_and_b32_e32 v77, 0xffff0000, v48
	v_and_b32_e32 v76, 0xffff0000, v56
	v_lshlrev_b32_e32 v75, 16, v49
	v_lshlrev_b32_e32 v74, 16, v57
	v_and_b32_e32 v73, 0xffff0000, v49
	v_and_b32_e32 v72, 0xffff0000, v57
	v_lshlrev_b32_e32 v71, 16, v50
	v_lshlrev_b32_e32 v70, 16, v58
	v_and_b32_e32 v69, 0xffff0000, v50
	v_and_b32_e32 v68, 0xffff0000, v58
	v_lshlrev_b32_e32 v67, 16, v51
	v_lshlrev_b32_e32 v66, 16, v59
	v_and_b32_e32 v47, 0xffff0000, v51
	v_and_b32_e32 v46, 0xffff0000, v59
	s_and_saveexec_b64 s[14:15], vcc
	s_cbranch_execz .LBB0_1309
	ds_read_b128 v[88:91], v253 offset:0
	ds_read_b128 v[92:95], v253 offset:64
	ds_read_b128 v[96:99], v253 offset:16
	ds_read_b128 v[100:103], v253 offset:80
	ds_read_b128 v[104:107], v253 offset:128
	ds_read_b128 v[108:111], v253 offset:192
	ds_read_b128 v[112:115], v253 offset:144
	ds_read_b128 v[116:119], v253 offset:208
	s_waitcnt lgkmcnt(7)
	v_mov_b32_e32 v0, v88
	s_waitcnt lgkmcnt(6)
	v_mov_b32_e32 v1, v92
	v_mov_b32_e32 v92, v89
	v_pk_mul_f32 v[92:93], v[92:93], v[44:45]
	v_mov_b32_e32 v88, v90
	v_mov_b32_e32 v89, v94
	v_mov_b32_e32 v94, v91
	s_waitcnt lgkmcnt(4)
	v_mov_b32_e32 v91, v100
	v_mov_b32_e32 v100, v97
	v_mov_b32_e32 v97, v102
	v_mov_b32_e32 v102, v99
	s_waitcnt lgkmcnt(2)
	v_mov_b32_e32 v99, v108
	v_mov_b32_e32 v108, v105
	v_pk_fma_f32 v[0:1], v[0:1], v[14:15], v[92:93]
	v_mov_b32_e32 v90, v96
	v_mov_b32_e32 v96, v98
	v_mov_b32_e32 v98, v104
	v_pk_mul_f32 v[108:109], v[108:109], v[76:77]
	v_pk_fma_f32 v[0:1], v[88:89], v[42:43], v[0:1]
	v_mov_b32_e32 v104, v106
	v_mov_b32_e32 v105, v110
	v_pk_fma_f32 v[92:93], v[98:99], v[64:65], v[108:109]
	v_pk_fma_f32 v[0:1], v[94:95], v[40:41], v[0:1]
	v_mov_b32_e32 v110, v107
	v_pk_fma_f32 v[88:89], v[104:105], v[74:75], v[92:93]
	v_pk_fma_f32 v[0:1], v[90:91], v[38:39], v[0:1]
	s_waitcnt lgkmcnt(1)
	v_mov_b32_e32 v106, v112
	s_waitcnt lgkmcnt(0)
	v_mov_b32_e32 v107, v116
	v_pk_fma_f32 v[88:89], v[110:111], v[72:73], v[88:89]
	v_pk_fma_f32 v[0:1], v[100:101], v[36:37], v[0:1]
	v_mov_b32_e32 v116, v113
	v_pk_fma_f32 v[88:89], v[106:107], v[70:71], v[88:89]
	v_pk_fma_f32 v[0:1], v[96:97], v[34:35], v[0:1]
	v_mov_b32_e32 v112, v114
	v_mov_b32_e32 v113, v118
	v_pk_fma_f32 v[88:89], v[116:117], v[68:69], v[88:89]
	v_pk_fma_f32 v[0:1], v[102:103], v[32:33], v[0:1]
	v_mov_b32_e32 v118, v115
	v_pk_fma_f32 v[88:89], v[112:113], v[66:67], v[88:89]
	v_add_f32_e32 v0, 0, v0
	v_add_f32_e32 v87, v0, v1
	v_pk_fma_f32 v[0:1], v[118:119], v[46:47], v[88:89]
	s_nop 0
	v_add_f32_e32 v0, v87, v0
	v_add_f32_e32 v87, v0, v1
.LBB0_1309:
	s_or_b64 exec, exec, s[14:15]
	ds_bpermute_b32 v0, v204, v87
	s_and_saveexec_b64 s[14:15], s[2:3]
	s_cbranch_execz .LBB0_1311
	ds_read_b128 v[88:91], v253 offset:256
	ds_read_b128 v[92:95], v253 offset:320
	ds_read_b128 v[96:99], v253 offset:272
	ds_read_b128 v[100:103], v253 offset:336
	ds_read_b128 v[104:107], v253 offset:384
	ds_read_b128 v[108:111], v253 offset:448
	ds_read_b128 v[112:115], v253 offset:400
	ds_read_b128 v[116:119], v253 offset:464
	s_waitcnt lgkmcnt(7)
	v_mov_b32_e32 v2, v88
	s_waitcnt lgkmcnt(6)
	v_mov_b32_e32 v3, v92
	v_mov_b32_e32 v92, v89
	v_pk_mul_f32 v[92:93], v[92:93], v[44:45]
	v_mov_b32_e32 v88, v90
	v_mov_b32_e32 v89, v94
	v_mov_b32_e32 v94, v91
	s_waitcnt lgkmcnt(4)
	v_mov_b32_e32 v91, v100
	v_mov_b32_e32 v100, v97
	v_mov_b32_e32 v97, v102
	v_mov_b32_e32 v102, v99
	s_waitcnt lgkmcnt(2)
	v_mov_b32_e32 v99, v108
	v_mov_b32_e32 v108, v105
	v_pk_fma_f32 v[2:3], v[2:3], v[14:15], v[92:93]
	v_mov_b32_e32 v90, v96
	v_mov_b32_e32 v96, v98
	v_mov_b32_e32 v98, v104
	v_pk_mul_f32 v[108:109], v[108:109], v[76:77]
	v_pk_fma_f32 v[2:3], v[88:89], v[42:43], v[2:3]
	v_mov_b32_e32 v104, v106
	v_mov_b32_e32 v105, v110
	v_pk_fma_f32 v[92:93], v[98:99], v[64:65], v[108:109]
	v_pk_fma_f32 v[2:3], v[94:95], v[40:41], v[2:3]
	v_mov_b32_e32 v110, v107
	v_pk_fma_f32 v[88:89], v[104:105], v[74:75], v[92:93]
	v_pk_fma_f32 v[2:3], v[90:91], v[38:39], v[2:3]
	s_waitcnt lgkmcnt(1)
	v_mov_b32_e32 v106, v112
	s_waitcnt lgkmcnt(0)
	v_mov_b32_e32 v107, v116
	v_pk_fma_f32 v[88:89], v[110:111], v[72:73], v[88:89]
	v_pk_fma_f32 v[2:3], v[100:101], v[36:37], v[2:3]
	v_mov_b32_e32 v116, v113
	v_pk_fma_f32 v[88:89], v[106:107], v[70:71], v[88:89]
	v_pk_fma_f32 v[2:3], v[96:97], v[34:35], v[2:3]
	v_mov_b32_e32 v112, v114
	v_mov_b32_e32 v113, v118
	v_pk_fma_f32 v[88:89], v[116:117], v[68:69], v[88:89]
	v_pk_fma_f32 v[2:3], v[102:103], v[32:33], v[2:3]
	v_mov_b32_e32 v118, v115
	v_pk_fma_f32 v[88:89], v[112:113], v[66:67], v[88:89]
	v_add_f32_e32 v1, 0, v2
	v_add_f32_e32 v1, v1, v3
	v_pk_fma_f32 v[2:3], v[118:119], v[46:47], v[88:89]
	s_nop 0
	v_add_f32_e32 v1, v1, v2
	v_add_f32_e32 v86, v1, v3
.LBB0_1311:
	s_or_b64 exec, exec, s[14:15]
	ds_bpermute_b32 v1, v204, v86
	v_mov_b32_e32 v3, 0
	v_mov_b32_e32 v2, 0
	s_and_saveexec_b64 s[2:3], s[4:5]
	s_cbranch_execz .LBB0_1313
	ds_read_b128 v[88:91], v253 offset:512
	ds_read_b128 v[92:95], v253 offset:576
	ds_read_b128 v[96:99], v253 offset:528
	ds_read_b128 v[100:103], v253 offset:592
	ds_read_b128 v[104:107], v253 offset:640
	ds_read_b128 v[108:111], v253 offset:704
	ds_read_b128 v[112:115], v253 offset:656
	ds_read_b128 v[116:119], v253 offset:720
	s_waitcnt lgkmcnt(7)
	v_mov_b32_e32 v4, v88
	s_waitcnt lgkmcnt(6)
	v_mov_b32_e32 v5, v92
	v_mov_b32_e32 v92, v89
	v_pk_mul_f32 v[92:93], v[92:93], v[44:45]
	v_mov_b32_e32 v88, v90
	v_mov_b32_e32 v89, v94
	v_mov_b32_e32 v94, v91
	s_waitcnt lgkmcnt(4)
	v_mov_b32_e32 v91, v100
	v_mov_b32_e32 v100, v97
	v_mov_b32_e32 v97, v102
	v_mov_b32_e32 v102, v99
	s_waitcnt lgkmcnt(2)
	v_mov_b32_e32 v99, v108
	v_mov_b32_e32 v108, v105
	v_pk_fma_f32 v[4:5], v[4:5], v[14:15], v[92:93]
	v_mov_b32_e32 v90, v96
	v_mov_b32_e32 v96, v98
	v_mov_b32_e32 v98, v104
	v_pk_mul_f32 v[108:109], v[108:109], v[76:77]
	v_pk_fma_f32 v[4:5], v[88:89], v[42:43], v[4:5]
	v_mov_b32_e32 v104, v106
	v_mov_b32_e32 v105, v110
	v_pk_fma_f32 v[92:93], v[98:99], v[64:65], v[108:109]
	v_pk_fma_f32 v[4:5], v[94:95], v[40:41], v[4:5]
	v_mov_b32_e32 v110, v107
	v_pk_fma_f32 v[88:89], v[104:105], v[74:75], v[92:93]
	v_pk_fma_f32 v[4:5], v[90:91], v[38:39], v[4:5]
	s_waitcnt lgkmcnt(1)
	v_mov_b32_e32 v106, v112
	s_waitcnt lgkmcnt(0)
	v_mov_b32_e32 v107, v116
	v_pk_fma_f32 v[88:89], v[110:111], v[72:73], v[88:89]
	v_pk_fma_f32 v[4:5], v[100:101], v[36:37], v[4:5]
	v_mov_b32_e32 v116, v113
	v_pk_fma_f32 v[88:89], v[106:107], v[70:71], v[88:89]
	v_pk_fma_f32 v[4:5], v[96:97], v[34:35], v[4:5]
	v_mov_b32_e32 v112, v114
	v_mov_b32_e32 v113, v118
	v_pk_fma_f32 v[88:89], v[116:117], v[68:69], v[88:89]
	v_pk_fma_f32 v[4:5], v[102:103], v[32:33], v[4:5]
	v_mov_b32_e32 v118, v115
	v_pk_fma_f32 v[88:89], v[112:113], v[66:67], v[88:89]
	v_add_f32_e32 v2, 0, v4
	v_add_f32_e32 v2, v2, v5
	v_pk_fma_f32 v[4:5], v[118:119], v[46:47], v[88:89]
	s_nop 0
	v_add_f32_e32 v2, v2, v4
	v_add_f32_e32 v2, v2, v5
.LBB0_1313:
	s_or_b64 exec, exec, s[2:3]
	ds_bpermute_b32 v4, v204, v2
	s_and_saveexec_b64 s[2:3], s[6:7]
	s_cbranch_execz .LBB0_1315
	ds_read_b128 v[88:91], v253 offset:768
	ds_read_b128 v[92:95], v253 offset:832
	ds_read_b128 v[96:99], v253 offset:784
	ds_read_b128 v[100:103], v253 offset:848
	ds_read_b128 v[104:107], v253 offset:896
	ds_read_b128 v[108:111], v253 offset:960
	ds_read_b128 v[112:115], v253 offset:912
	ds_read_b128 v[116:119], v253 offset:976
	s_waitcnt lgkmcnt(7)
	v_mov_b32_e32 v6, v88
	s_waitcnt lgkmcnt(6)
	v_mov_b32_e32 v7, v92
	v_mov_b32_e32 v92, v89
	v_pk_mul_f32 v[92:93], v[92:93], v[44:45]
	v_mov_b32_e32 v88, v90
	v_mov_b32_e32 v89, v94
	v_mov_b32_e32 v94, v91
	s_waitcnt lgkmcnt(4)
	v_mov_b32_e32 v91, v100
	v_mov_b32_e32 v100, v97
	v_mov_b32_e32 v97, v102
	v_mov_b32_e32 v102, v99
	s_waitcnt lgkmcnt(2)
	v_mov_b32_e32 v99, v108
	v_mov_b32_e32 v108, v105
	v_pk_fma_f32 v[6:7], v[6:7], v[14:15], v[92:93]
	v_mov_b32_e32 v90, v96
	v_mov_b32_e32 v96, v98
	v_mov_b32_e32 v98, v104
	v_pk_mul_f32 v[108:109], v[108:109], v[76:77]
	v_pk_fma_f32 v[6:7], v[88:89], v[42:43], v[6:7]
	v_mov_b32_e32 v104, v106
	v_mov_b32_e32 v105, v110
	v_pk_fma_f32 v[92:93], v[98:99], v[64:65], v[108:109]
	v_pk_fma_f32 v[6:7], v[94:95], v[40:41], v[6:7]
	v_mov_b32_e32 v110, v107
	v_pk_fma_f32 v[88:89], v[104:105], v[74:75], v[92:93]
	v_pk_fma_f32 v[6:7], v[90:91], v[38:39], v[6:7]
	s_waitcnt lgkmcnt(1)
	v_mov_b32_e32 v106, v112
	s_waitcnt lgkmcnt(0)
	v_mov_b32_e32 v107, v116
	v_pk_fma_f32 v[88:89], v[110:111], v[72:73], v[88:89]
	v_pk_fma_f32 v[6:7], v[100:101], v[36:37], v[6:7]
	v_mov_b32_e32 v116, v113
	v_pk_fma_f32 v[88:89], v[106:107], v[70:71], v[88:89]
	v_pk_fma_f32 v[6:7], v[96:97], v[34:35], v[6:7]
	v_mov_b32_e32 v112, v114
	v_mov_b32_e32 v113, v118
	v_pk_fma_f32 v[88:89], v[116:117], v[68:69], v[88:89]
	v_pk_fma_f32 v[6:7], v[102:103], v[32:33], v[6:7]
	v_mov_b32_e32 v118, v115
	v_pk_fma_f32 v[88:89], v[112:113], v[66:67], v[88:89]
	v_add_f32_e32 v3, 0, v6
	v_add_f32_e32 v3, v3, v7
	v_pk_fma_f32 v[6:7], v[118:119], v[46:47], v[88:89]
	s_nop 0
	v_add_f32_e32 v3, v3, v6
	v_add_f32_e32 v3, v3, v7
.LBB0_1315:
	s_or_b64 exec, exec, s[2:3]
	ds_bpermute_b32 v5, v204, v3
	v_mov_b32_e32 v7, 0
	v_mov_b32_e32 v6, 0
	s_and_saveexec_b64 s[2:3], s[8:9]
	s_cbranch_execz .LBB0_1317
	ds_read_b128 v[88:91], v253 offset:1024
	ds_read_b128 v[92:95], v253 offset:1088
	ds_read_b128 v[96:99], v253 offset:1040
	ds_read_b128 v[100:103], v253 offset:1104
	ds_read_b128 v[104:107], v253 offset:1152
	ds_read_b128 v[108:111], v253 offset:1216
	ds_read_b128 v[112:115], v253 offset:1168
	ds_read_b128 v[116:119], v253 offset:1232
	s_waitcnt lgkmcnt(7)
	v_mov_b32_e32 v8, v88
	s_waitcnt lgkmcnt(6)
	v_mov_b32_e32 v9, v92
	v_mov_b32_e32 v92, v89
	v_pk_mul_f32 v[92:93], v[92:93], v[44:45]
	v_mov_b32_e32 v88, v90
	v_mov_b32_e32 v89, v94
	v_mov_b32_e32 v94, v91
	s_waitcnt lgkmcnt(4)
	v_mov_b32_e32 v91, v100
	v_mov_b32_e32 v100, v97
	v_mov_b32_e32 v97, v102
	v_mov_b32_e32 v102, v99
	s_waitcnt lgkmcnt(2)
	v_mov_b32_e32 v99, v108
	v_mov_b32_e32 v108, v105
	v_pk_fma_f32 v[8:9], v[8:9], v[14:15], v[92:93]
	v_mov_b32_e32 v90, v96
	v_mov_b32_e32 v96, v98
	v_mov_b32_e32 v98, v104
	v_pk_mul_f32 v[108:109], v[108:109], v[76:77]
	v_pk_fma_f32 v[8:9], v[88:89], v[42:43], v[8:9]
	v_mov_b32_e32 v104, v106
	v_mov_b32_e32 v105, v110
	v_pk_fma_f32 v[92:93], v[98:99], v[64:65], v[108:109]
	v_pk_fma_f32 v[8:9], v[94:95], v[40:41], v[8:9]
	v_mov_b32_e32 v110, v107
	v_pk_fma_f32 v[88:89], v[104:105], v[74:75], v[92:93]
	v_pk_fma_f32 v[8:9], v[90:91], v[38:39], v[8:9]
	s_waitcnt lgkmcnt(1)
	v_mov_b32_e32 v106, v112
	s_waitcnt lgkmcnt(0)
	v_mov_b32_e32 v107, v116
	v_pk_fma_f32 v[88:89], v[110:111], v[72:73], v[88:89]
	v_pk_fma_f32 v[8:9], v[100:101], v[36:37], v[8:9]
	v_mov_b32_e32 v116, v113
	v_pk_fma_f32 v[88:89], v[106:107], v[70:71], v[88:89]
	v_pk_fma_f32 v[8:9], v[96:97], v[34:35], v[8:9]
	v_mov_b32_e32 v112, v114
	v_mov_b32_e32 v113, v118
	v_pk_fma_f32 v[88:89], v[116:117], v[68:69], v[88:89]
	v_pk_fma_f32 v[8:9], v[102:103], v[32:33], v[8:9]
	v_mov_b32_e32 v118, v115
	v_pk_fma_f32 v[88:89], v[112:113], v[66:67], v[88:89]
	v_add_f32_e32 v6, 0, v8
	v_add_f32_e32 v6, v6, v9
	v_pk_fma_f32 v[8:9], v[118:119], v[46:47], v[88:89]
	s_nop 0
	v_add_f32_e32 v6, v6, v8
	v_add_f32_e32 v6, v6, v9
.LBB0_1317:
	s_or_b64 exec, exec, s[2:3]
	ds_bpermute_b32 v8, v204, v6
	s_and_saveexec_b64 s[2:3], s[10:11]
	s_cbranch_execz .LBB0_1319
	ds_read_b128 v[88:91], v253 offset:1280
	ds_read_b128 v[92:95], v253 offset:1344
	ds_read_b128 v[96:99], v253 offset:1296
	ds_read_b128 v[100:103], v253 offset:1360
	ds_read_b128 v[104:107], v253 offset:1408
	ds_read_b128 v[108:111], v253 offset:1472
	ds_read_b128 v[112:115], v253 offset:1424
	ds_read_b128 v[116:119], v253 offset:1488
	s_waitcnt lgkmcnt(7)
	v_mov_b32_e32 v10, v88
	s_waitcnt lgkmcnt(6)
	v_mov_b32_e32 v11, v92
	v_mov_b32_e32 v92, v89
	v_pk_mul_f32 v[92:93], v[92:93], v[44:45]
	v_mov_b32_e32 v88, v90
	v_mov_b32_e32 v89, v94
	v_mov_b32_e32 v94, v91
	s_waitcnt lgkmcnt(4)
	v_mov_b32_e32 v91, v100
	v_mov_b32_e32 v100, v97
	v_mov_b32_e32 v97, v102
	v_mov_b32_e32 v102, v99
	s_waitcnt lgkmcnt(2)
	v_mov_b32_e32 v99, v108
	v_mov_b32_e32 v108, v105
	v_pk_fma_f32 v[10:11], v[10:11], v[14:15], v[92:93]
	v_mov_b32_e32 v90, v96
	v_mov_b32_e32 v96, v98
	v_mov_b32_e32 v98, v104
	v_pk_mul_f32 v[108:109], v[108:109], v[76:77]
	v_pk_fma_f32 v[10:11], v[88:89], v[42:43], v[10:11]
	v_mov_b32_e32 v104, v106
	v_mov_b32_e32 v105, v110
	v_pk_fma_f32 v[92:93], v[98:99], v[64:65], v[108:109]
	v_pk_fma_f32 v[10:11], v[94:95], v[40:41], v[10:11]
	v_mov_b32_e32 v110, v107
	v_pk_fma_f32 v[88:89], v[104:105], v[74:75], v[92:93]
	v_pk_fma_f32 v[10:11], v[90:91], v[38:39], v[10:11]
	s_waitcnt lgkmcnt(1)
	v_mov_b32_e32 v106, v112
	s_waitcnt lgkmcnt(0)
	v_mov_b32_e32 v107, v116
	v_pk_fma_f32 v[88:89], v[110:111], v[72:73], v[88:89]
	v_pk_fma_f32 v[10:11], v[100:101], v[36:37], v[10:11]
	v_mov_b32_e32 v116, v113
	v_pk_fma_f32 v[88:89], v[106:107], v[70:71], v[88:89]
	v_pk_fma_f32 v[10:11], v[96:97], v[34:35], v[10:11]
	v_mov_b32_e32 v112, v114
	v_mov_b32_e32 v113, v118
	v_pk_fma_f32 v[88:89], v[116:117], v[68:69], v[88:89]
	v_pk_fma_f32 v[10:11], v[102:103], v[32:33], v[10:11]
	v_mov_b32_e32 v118, v115
	v_pk_fma_f32 v[88:89], v[112:113], v[66:67], v[88:89]
	v_add_f32_e32 v7, 0, v10
	v_add_f32_e32 v7, v7, v11
	v_pk_fma_f32 v[10:11], v[118:119], v[46:47], v[88:89]
	s_nop 0
	v_add_f32_e32 v7, v7, v10
	v_add_f32_e32 v7, v7, v11
.LBB0_1319:
	s_or_b64 exec, exec, s[2:3]
	ds_bpermute_b32 v9, v204, v7
	v_mov_b32_e32 v10, 0
	s_and_saveexec_b64 s[2:3], s[12:13]
	s_cbranch_execz .LBB0_1321
	ds_read_b128 v[88:91], v253 offset:1536
	ds_read_b128 v[92:95], v253 offset:1600
	ds_read_b128 v[96:99], v253 offset:1552
	ds_read_b128 v[100:103], v253 offset:1616
	ds_read_b128 v[104:107], v253 offset:1664
	ds_read_b128 v[108:111], v253 offset:1728
	ds_read_b128 v[112:115], v253 offset:1680
	s_nop 0
	ds_read_b128 v[10:13], v253 offset:1744
	s_waitcnt lgkmcnt(7)
	v_mov_b32_e32 v116, v88
	s_waitcnt lgkmcnt(6)
	v_mov_b32_e32 v117, v92
	v_mov_b32_e32 v92, v89
	v_pk_mul_f32 v[44:45], v[92:93], v[44:45]
	v_mov_b32_e32 v88, v90
	v_mov_b32_e32 v89, v94
	v_mov_b32_e32 v94, v91
	s_waitcnt lgkmcnt(4)
	v_mov_b32_e32 v91, v100
	v_mov_b32_e32 v100, v97
	v_mov_b32_e32 v97, v102
	v_mov_b32_e32 v102, v99
	s_waitcnt lgkmcnt(2)
	v_mov_b32_e32 v99, v108
	v_mov_b32_e32 v108, v105
	v_pk_fma_f32 v[14:15], v[116:117], v[14:15], v[44:45]
	v_mov_b32_e32 v90, v96
	v_mov_b32_e32 v96, v98
	v_mov_b32_e32 v98, v104
	v_pk_mul_f32 v[76:77], v[108:109], v[76:77]
	v_pk_fma_f32 v[14:15], v[88:89], v[42:43], v[14:15]
	v_mov_b32_e32 v104, v106
	v_mov_b32_e32 v105, v110
	v_pk_fma_f32 v[44:45], v[98:99], v[64:65], v[76:77]
	v_pk_fma_f32 v[14:15], v[94:95], v[40:41], v[14:15]
	v_mov_b32_e32 v110, v107
	v_pk_fma_f32 v[42:43], v[104:105], v[74:75], v[44:45]
	v_pk_fma_f32 v[14:15], v[90:91], v[38:39], v[14:15]
	s_waitcnt lgkmcnt(1)
	v_mov_b32_e32 v106, v112
	s_waitcnt lgkmcnt(0)
	v_mov_b32_e32 v107, v10
	v_pk_fma_f32 v[40:41], v[110:111], v[72:73], v[42:43]
	v_pk_fma_f32 v[14:15], v[100:101], v[36:37], v[14:15]
	v_mov_b32_e32 v10, v113
	v_pk_fma_f32 v[38:39], v[106:107], v[70:71], v[40:41]
	v_pk_fma_f32 v[14:15], v[96:97], v[34:35], v[14:15]
	v_mov_b32_e32 v112, v114
	v_mov_b32_e32 v113, v12
	v_pk_fma_f32 v[10:11], v[10:11], v[68:69], v[38:39]
	v_pk_fma_f32 v[14:15], v[102:103], v[32:33], v[14:15]
	v_mov_b32_e32 v12, v115
	v_pk_fma_f32 v[10:11], v[112:113], v[66:67], v[10:11]
	v_add_f32_e32 v14, 0, v14
	v_add_f32_e32 v14, v14, v15
	v_pk_fma_f32 v[10:11], v[12:13], v[46:47], v[10:11]
	s_nop 0
	v_add_f32_e32 v10, v14, v10
	v_add_f32_e32 v10, v10, v11

.LBB0_1326:
	s_lshr_b32 s0, s0, 2
	s_lshl_b32 s0, 1, s0
	v_and_b32_e32 v64, s0, v205
	v_mov_b32_e32 v168, 0
	v_cmp_ne_u32_e64 s[4:5], 0, v64
	v_cmp_le_i32_e32 vcc, s18, v206
	v_mov_b32_e32 v64, 0
	s_and_saveexec_b64 s[2:3], vcc
	v_cndmask_b32_e64 v64, 0, 1, s[4:5]
	v_cmp_ne_u32_e32 vcc, 0, v64
	s_cmp_lg_u64 vcc, 0
	s_cselect_b64 s[6:7], -1, 0
	v_cndmask_b32_e64 v64, 0, 1, s[6:7]
	s_or_b64 exec, exec, s[2:3]
	v_and_b32_e32 v65, s0, v175
	v_cmp_ne_u32_e32 vcc, 0, v65
	v_cmp_le_i32_e64 s[2:3], s18, v207
	s_and_saveexec_b64 s[6:7], s[2:3]
	v_cndmask_b32_e64 v65, 0, 1, vcc
	v_cmp_ne_u32_e64 s[2:3], 0, v65
	s_cmp_lg_u64 s[2:3], 0
	s_cselect_b64 s[0:1], -1, 0
	v_cndmask_b32_e64 v168, 0, 1, s[0:1]
	s_or_b64 exec, exec, s[6:7]
	v_and_b32_e32 v65, 1, v64
	v_cmp_eq_u32_e64 s[6:7], 1, v65
	v_and_b32_e32 v65, 1, v168
	v_cmp_eq_u32_e64 s[2:3], 1, v65
	s_or_b64 s[0:1], s[6:7], s[2:3]
	s_and_saveexec_b64 s[12:13], s[0:1]
	s_cbranch_execz .LBB0_1338
	v_add_u32_e32 v65, s19, v208
	v_subrev_u32_e32 v66, 63, v65
	v_cmp_gt_i32_e64 s[8:9], s87, v66
	v_cndmask_b32_e64 v215, 0, v202, s[4:5]
	s_cmp_eq_u32 s97, 0
	v_cndmask_b32_e64 v66, 0, v198, s[8:9]
	v_or3_b32 v216, v215, v66, v64
	s_waitcnt lgkmcnt(8)
	v_cndmask_b32_e64 v64, v203, v212, s[4:5]
	v_cndmask_b32_e64 v64, v64, 0, s[8:9]
	s_cselect_b64 s[8:9], -1, 0
	s_and_b64 s[0:1], s[8:9], exec
	s_cselect_b32 s0, 0, 0x2400
	v_subrev_u32_e32 v65, 31, v65
	v_add_u32_e32 v217, s0, v209
	v_cmp_gt_i32_e64 s[4:5], s87, v65
	v_cndmask_b32_e32 v65, v203, v212, vcc
	ds_read_b128 v[186:189], v217 offset:4608
	ds_read_b128 v[190:193], v217
	ds_read_b128 v[194:197], v217 offset:32
	v_cndmask_b32_e64 v65, v65, 0, s[4:5]
	v_cndmask_b32_e64 v80, v203, v64, s[6:7]
	v_cndmask_b32_e64 v64, v203, v65, s[2:3]
	v_mov_b32_e32 v81, v80
	v_mov_b32_e32 v82, v80
	v_mov_b32_e32 v83, v80
	v_mov_b32_e32 v84, v80
	v_mov_b32_e32 v85, v80
	v_mov_b32_e32 v86, v80
	v_mov_b32_e32 v87, v80
	v_mov_b32_e32 v88, v80
	v_mov_b32_e32 v89, v80
	v_mov_b32_e32 v90, v80
	v_mov_b32_e32 v91, v80
	v_mov_b32_e32 v92, v80
	v_mov_b32_e32 v93, v80
	v_mov_b32_e32 v94, v80
	v_mov_b32_e32 v95, v80
	v_mov_b32_e32 v65, v64
	v_mov_b32_e32 v66, v64
	v_mov_b32_e32 v67, v64
	v_mov_b32_e32 v68, v64
	v_mov_b32_e32 v69, v64
	v_mov_b32_e32 v70, v64
	v_mov_b32_e32 v71, v64
	v_mov_b32_e32 v72, v64
	v_mov_b32_e32 v73, v64
	v_mov_b32_e32 v74, v64
	v_mov_b32_e32 v75, v64
	v_mov_b32_e32 v76, v64
	v_mov_b32_e32 v77, v64
	v_mov_b32_e32 v78, v64
	v_mov_b32_e32 v79, v64
	s_waitcnt lgkmcnt(1)
	v_mfma_f32_32x32x16_bf16 v[96:111], v[190:193], v[128:131], v[80:95]
	v_mfma_f32_32x32x16_bf16 v[112:127], v[190:193], v[148:151], v[64:79]
	v_mfma_f32_32x32x16_bf16 v[80:95], v[186:189], v[128:131], v[80:95]
	v_mfma_f32_32x32x16_bf16 v[64:79], v[186:189], v[148:151], v[64:79]
	ds_read_b128 v[186:189], v217 offset:4640
	s_waitcnt lgkmcnt(1)
	v_mfma_f32_32x32x16_bf16 v[96:111], v[194:197], v[132:135], v[96:111]
	v_mfma_f32_32x32x16_bf16 v[112:127], v[194:197], v[140:143], v[112:127]
	s_waitcnt lgkmcnt(0)
	v_mfma_f32_32x32x16_bf16 v[80:95], v[186:189], v[132:135], v[80:95]
	v_mfma_f32_32x32x16_bf16 v[64:79], v[186:189], v[140:143], v[64:79]
	ds_read_b128 v[186:189], v217 offset:64
	ds_read_b128 v[190:193], v217 offset:4672
	s_waitcnt lgkmcnt(1)
	v_mfma_f32_32x32x16_bf16 v[96:111], v[186:189], v[136:139], v[96:111]
	v_mfma_f32_32x32x16_bf16 v[112:127], v[186:189], v[144:147], v[112:127]
	s_waitcnt lgkmcnt(0)
	v_mfma_f32_32x32x16_bf16 v[80:95], v[190:193], v[136:139], v[80:95]
	v_mfma_f32_32x32x16_bf16 v[64:79], v[190:193], v[144:147], v[64:79]
	ds_read_b128 v[186:189], v217 offset:96
	ds_read_b128 v[190:193], v217 offset:4704
	s_waitcnt lgkmcnt(1)
	v_mfma_f32_32x32x16_bf16 v[96:111], v[186:189], v[152:155], v[96:111]
	v_mfma_f32_32x32x16_bf16 v[112:127], v[186:189], v[156:159], v[112:127]
	v_cndmask_b32_e64 v186, v215, v216, s[6:7]
	v_and_b32_e32 v187, 0x100, v186
	v_cmp_ne_u32_e64 s[6:7], 0, v187
	s_waitcnt lgkmcnt(0)
	v_mfma_f32_32x32x16_bf16 v[80:95], v[190:193], v[152:155], v[80:95]
	v_mfma_f32_32x32x16_bf16 v[64:79], v[190:193], v[156:159], v[64:79]
	v_add_u32_e32 v190, s19, v211
	v_min_i32_e32 v223, 0x80, v190
	v_add_u32_e32 v222, -1, v190
	v_add_u32_e32 v221, -2, v190
	v_add_u32_e32 v220, -3, v190
	v_add_u32_e32 v219, -8, v190
	v_add_u32_e32 v218, -9, v190
	v_add_u32_e32 v217, -10, v190
	v_add_u32_e32 v216, -11, v190
	v_add_u32_e32 v215, -16, v190
	v_subrev_u32_e32 v197, 17, v190
	v_subrev_u32_e32 v196, 18, v190
	v_subrev_u32_e32 v195, 19, v190
	v_subrev_u32_e32 v194, 24, v190
	v_subrev_u32_e32 v193, 25, v190
	v_subrev_u32_e32 v192, 26, v190
	v_subrev_u32_e32 v191, 27, v190
	s_and_saveexec_b64 s[14:15], s[6:7]
	s_cbranch_execz .LBB0_1333
	v_lshl_add_u32 v224, v190, 2, s91
	v_and_b32_e32 v186, 0x10000, v186
	v_cmp_ne_u32_e64 s[6:7], 0, v186
	v_mov_b32_e32 v225, 0x1d000
	s_nop 1
	v_cndmask_b32_e64 v224, v225, v224, s[6:7]
	ds_read_b32 v226, v224 offset:236
	ds_read_b32 v227, v224 offset:232
	ds_read_b32 v228, v224 offset:228
	ds_read_b32 v229, v224 offset:224
	ds_read_b32 v230, v224 offset:204
	ds_read_b32 v231, v224 offset:200
	ds_read_b32 v232, v224 offset:196
	ds_read_b32 v233, v224 offset:192
	ds_read_b32 v234, v224 offset:172
	ds_read_b32 v235, v224 offset:168
	ds_read_b32 v236, v224 offset:164
	ds_read_b32 v237, v224 offset:160
	ds_read_b32 v238, v224 offset:140
	ds_read_b32 v239, v224 offset:136
	ds_read_b32 v240, v224 offset:132
	ds_read_b32 v241, v224 offset:128
	ds_read_b32 v242, v224 offset:108
	ds_read_b32 v243, v224 offset:104
	ds_read_b32 v244, v224 offset:100
	ds_read_b32 v245, v224 offset:96
	ds_read_b32 v246, v224 offset:76
	ds_read_b32 v247, v224 offset:72
	ds_read_b32 v248, v224 offset:68
	ds_read_b32 v249, v224 offset:64
	ds_read_b32 v250, v224 offset:44
	ds_read_b32 v251, v224 offset:40
	ds_read_b32 v252, v224 offset:36
	ds_read_b32 v253, v224 offset:32
	s_waitcnt lgkmcnt(12)
	v_pk_add_f32 v[96:97], v[96:97], v[226:227]
	v_pk_add_f32 v[98:99], v[98:99], v[228:229]
	v_pk_add_f32 v[100:101], v[100:101], v[230:231]
	v_pk_add_f32 v[102:103], v[102:103], v[232:233]
	v_pk_add_f32 v[104:105], v[104:105], v[234:235]
	v_pk_add_f32 v[106:107], v[106:107], v[236:237]
	v_pk_add_f32 v[108:109], v[108:109], v[238:239]
	v_pk_add_f32 v[110:111], v[110:111], v[240:241]
	ds_read_b32 v226, v224 offset:12
	ds_read_b32 v227, v224 offset:8
	ds_read_b32 v228, v224 offset:4
	ds_read_b32 v229, v224 offset:0
	s_waitcnt lgkmcnt(4)
	v_pk_add_f32 v[80:81], v[80:81], v[242:243]
	v_pk_add_f32 v[82:83], v[82:83], v[244:245]
	v_pk_add_f32 v[84:85], v[84:85], v[246:247]
	v_pk_add_f32 v[86:87], v[86:87], v[248:249]
	v_pk_add_f32 v[88:89], v[88:89], v[250:251]
	v_pk_add_f32 v[90:91], v[90:91], v[252:253]
	s_waitcnt lgkmcnt(0)
	v_pk_add_f32 v[92:93], v[92:93], v[226:227]
	v_pk_add_f32 v[94:95], v[94:95], v[228:229]
.LBB0_1333:
	s_or_b64 exec, exec, s[14:15]
	v_cndmask_b32_e32 v186, 0, v202, vcc
	v_cndmask_b32_e64 v187, 0, v198, s[4:5]
	v_or3_b32 v168, v186, v187, v168
	v_cndmask_b32_e64 v168, v186, v168, s[2:3]
	v_and_b32_e32 v186, 0x100, v168
	v_cmp_ne_u32_e32 vcc, 0, v186
	s_and_saveexec_b64 s[2:3], vcc
	s_cbranch_execz .LBB0_1335
	v_lshl_add_u32 v224, v190, 2, s32
	v_and_b32_e32 v187, 0x10000, v168
	v_cmp_ne_u32_e32 vcc, 0, v187
	v_mov_b32_e32 v225, 0x1d000
	s_nop 1
	v_cndmask_b32_e32 v224, v225, v224, vcc
	ds_read_b32 v226, v224 offset:236
	ds_read_b32 v227, v224 offset:232
	ds_read_b32 v228, v224 offset:228
	ds_read_b32 v229, v224 offset:224
	ds_read_b32 v230, v224 offset:204
	ds_read_b32 v231, v224 offset:200
	ds_read_b32 v232, v224 offset:196
	ds_read_b32 v233, v224 offset:192
	ds_read_b32 v234, v224 offset:172
	ds_read_b32 v235, v224 offset:168
	ds_read_b32 v236, v224 offset:164
	ds_read_b32 v237, v224 offset:160
	ds_read_b32 v238, v224 offset:140
	ds_read_b32 v239, v224 offset:136
	ds_read_b32 v240, v224 offset:132
	ds_read_b32 v241, v224 offset:128
	ds_read_b32 v242, v224 offset:108
	ds_read_b32 v243, v224 offset:104
	ds_read_b32 v244, v224 offset:100
	ds_read_b32 v245, v224 offset:96
	ds_read_b32 v246, v224 offset:76
	ds_read_b32 v247, v224 offset:72
	ds_read_b32 v248, v224 offset:68
	ds_read_b32 v249, v224 offset:64
	ds_read_b32 v250, v224 offset:44
	ds_read_b32 v251, v224 offset:40
	ds_read_b32 v252, v224 offset:36
	ds_read_b32 v253, v224 offset:32
	s_waitcnt lgkmcnt(12)
	v_pk_add_f32 v[112:113], v[112:113], v[226:227]
	v_pk_add_f32 v[114:115], v[114:115], v[228:229]
	v_pk_add_f32 v[116:117], v[116:117], v[230:231]
	v_pk_add_f32 v[118:119], v[118:119], v[232:233]
	v_pk_add_f32 v[120:121], v[120:121], v[234:235]
	v_pk_add_f32 v[122:123], v[122:123], v[236:237]
	v_pk_add_f32 v[124:125], v[124:125], v[238:239]
	v_pk_add_f32 v[126:127], v[126:127], v[240:241]
	ds_read_b32 v226, v224 offset:12
	ds_read_b32 v227, v224 offset:8
	ds_read_b32 v228, v224 offset:4
	ds_read_b32 v229, v224 offset:0
	s_waitcnt lgkmcnt(4)
	v_pk_add_f32 v[64:65], v[64:65], v[242:243]
	v_pk_add_f32 v[66:67], v[66:67], v[244:245]
	v_pk_add_f32 v[68:69], v[68:69], v[246:247]
	v_pk_add_f32 v[70:71], v[70:71], v[248:249]
	v_pk_add_f32 v[72:73], v[72:73], v[250:251]
	v_pk_add_f32 v[74:75], v[74:75], v[252:253]
	s_waitcnt lgkmcnt(0)
	v_pk_add_f32 v[76:77], v[76:77], v[226:227]
	v_pk_add_f32 v[78:79], v[78:79], v[228:229]

.LBB0_1476:
	s_cmp_lt_i32 s28, 17
	s_cselect_b64 s[0:1], -1, 0
	s_cmp_gt_i32 s29, 16
	s_cselect_b64 s[2:3], -1, 0
	s_and_b64 s[0:1], s[0:1], s[2:3]
	s_andn2_b64 vcc, exec, s[0:1]
	s_cbranch_vccnz .LBB0_1542
	s_mov_b64 s[8:9], exec
	v_readlane_b32 s0, v254, 4
	v_lshrrev_b32_e32 v0, 6, v200
	s_lshl_b32 s3, s30, 3
	v_readfirstlane_b32 s2, v0
	v_mbcnt_lo_u32_b32 v0, -1, 0
	v_mbcnt_hi_u32_b32 v0, -1, v0
	s_add_i32 s2, s2, s0
	s_cmp_ge_i32 s2, 0x10000
	s_cbranch_scc1 .Llnb1_done
	v_lshlrev_b32_e32 v1, 3, v0
	v_lshlrev_b32_e32 v0, 4, v0
	s_add_u32 s4, s36, 4096
	s_addc_u32 s5, s37, 0
	s_add_u32 s6, s38, 4096
	s_addc_u32 s7, s39, 0
	global_load_dwordx4 v[80:83], v0, s[4:5] offset:0
	global_load_dwordx4 v[84:87], v0, s[4:5] offset:1024
	global_load_dwordx4 v[88:91], v0, s[4:5] offset:2048
	global_load_dwordx4 v[92:95], v0, s[4:5] offset:3072
	global_load_dwordx4 v[96:99], v0, s[6:7] offset:0
	global_load_dwordx4 v[100:103], v0, s[6:7] offset:1024
	global_load_dwordx4 v[104:107], v0, s[6:7] offset:2048
	global_load_dwordx4 v[108:111], v0, s[6:7] offset:3072
	s_add_u32 s10, s26, 0x6000000
	s_addc_u32 s11, s27, 0
	v_mov_b32_e32 v112, 0x3727c5ac
	s_add_i32 s12, s2, s3
	s_cmp_lt_i32 s12, 0x10000
	s_cselect_b32 s13, s12, s2
	s_lshl_b32 s4, s2, 12
	s_add_u32 s4, s24, s4
	s_addc_u32 s5, s25, 0
	s_lshl_b32 s6, s13, 12
	s_add_u32 s6, s24, s6
	s_addc_u32 s7, s25, 0
	global_load_dwordx4 v[48:51], v0, s[4:5] offset:0
	global_load_dwordx4 v[52:55], v0, s[4:5] offset:1024
	global_load_dwordx4 v[56:59], v0, s[4:5] offset:2048
	global_load_dwordx4 v[60:63], v0, s[4:5] offset:3072
	global_load_dwordx4 v[64:67], v0, s[6:7] offset:0
	global_load_dwordx4 v[68:71], v0, s[6:7] offset:1024
	global_load_dwordx4 v[72:75], v0, s[6:7] offset:2048
	global_load_dwordx4 v[76:79], v0, s[6:7] offset:3072
	s_waitcnt vmcnt(0)
	s_branch .Llnb1_enter

.Llnb1_done:
.LBB0_1488:
	s_or_b64 exec, exec, s[8:9]
	s_cmp_lt_i32 s29, 18
	s_cbranch_scc1 .LBB0_1542
	s_waitcnt vmcnt(0)
	s_waitcnt vmcnt(0) lgkmcnt(0)
	s_barrier
	s_mov_b64 s[2:3], exec
	v_readlane_b32 s0, v254, 1
	v_readlane_b32 s1, v254, 2
	s_and_b64 s[0:1], s[2:3], s[0:1]
	s_mov_b64 exec, s[0:1]
	s_cbranch_execz .LBB0_1541
	s_add_i32 s0, 0, 0x20400
	v_mov_b32_e32 v0, s0
	s_waitcnt vmcnt(0) expcnt(0) lgkmcnt(0)
	ds_read_b32 v2, v0
	s_add_i32 s0, 0, 0x20404
	v_mov_b32_e32 v0, s0
	ds_read_b32 v0, v0
	s_waitcnt lgkmcnt(1)
	v_cmp_ne_u32_e32 vcc, 0, v2
	s_cbranch_vccnz .LBB0_1505
	s_add_u32 s4, s26, 0x3300200
	s_addc_u32 s5, s27, 0
	s_add_u32 s6, s26, 0x3300400
	s_addc_u32 s7, s27, 0
	s_add_u32 s8, s26, 0x3300500
	s_addc_u32 s9, s27, 0
	s_add_u32 s10, s26, 0x3300600
	s_addc_u32 s11, s27, 0
	s_add_u32 s12, s26, 0x3300700
	s_addc_u32 s13, s27, 0
	s_add_u32 s14, s26, 0x3300800
	s_addc_u32 s15, s27, 0
	s_add_u32 s18, s26, 0x3300900
	s_addc_u32 s19, s27, 0
	s_add_u32 s20, s26, 0x3300a00
	s_addc_u32 s21, s27, 0
	s_add_u32 s34, s26, 0x3300b00
	s_addc_u32 s35, s27, 0
	s_add_u32 s36, s26, 0x3300c00
	s_addc_u32 s37, s27, 0
	s_add_u32 s38, s26, 0x3300d00
	s_addc_u32 s39, s27, 0
	s_add_u32 s44, s26, 0x3300e00
	s_addc_u32 s45, s27, 0
	s_add_u32 s50, s26, 0x3300f00
	s_addc_u32 s51, s27, 0
	s_add_u32 s52, s26, 0x3301000
	s_addc_u32 s53, s27, 0
	s_add_u32 s54, s26, 0x3301100
	s_addc_u32 s55, s27, 0
	s_add_u32 s56, s26, 0x3301200
	v_readlane_b32 s0, v254, 0
	s_addc_u32 s57, s27, 0
	s_mul_i32 s0, s31, s0
	s_add_u32 s58, s26, 0x3301300
	s_mul_i32 s0, s0, s30
	s_addc_u32 s59, s27, 0
	s_mov_b32 s1, 1
	v_mov_b32_e32 v16, 0
	s_branch .LBB0_1493

.LBB0_1765:
	s_cmp_lt_i32 s28, 21
	s_cselect_b64 s[0:1], -1, 0
	s_cmp_gt_i32 s29, 20
	s_cselect_b64 s[2:3], -1, 0
	s_and_b64 s[0:1], s[0:1], s[2:3]
	s_andn2_b64 vcc, exec, s[0:1]
	s_cbranch_vccnz .LBB0_1833
	s_mov_b64 s[10:11], exec
	v_readlane_b32 s0, v254, 4
	v_lshrrev_b32_e32 v0, 6, v200
	s_lshl_b32 s3, s30, 3
	v_readfirstlane_b32 s2, v0
	v_mbcnt_lo_u32_b32 v0, -1, 0
	v_mbcnt_hi_u32_b32 v0, -1, v0
	s_add_i32 s2, s2, s0
	s_cmp_ge_i32 s2, 0x10000
	s_cbranch_scc1 .Llnb2_done
	v_lshlrev_b32_e32 v1, 3, v0
	v_lshlrev_b32_e32 v0, 4, v0
	s_add_u32 s4, s40, 4096
	s_addc_u32 s5, s41, 0
	s_add_u32 s6, s42, 4096
	s_addc_u32 s7, s43, 0
	global_load_dwordx4 v[80:83], v0, s[4:5] offset:0
	global_load_dwordx4 v[84:87], v0, s[4:5] offset:1024
	global_load_dwordx4 v[88:91], v0, s[4:5] offset:2048
	global_load_dwordx4 v[92:95], v0, s[4:5] offset:3072
	global_load_dwordx4 v[96:99], v0, s[6:7] offset:0
	global_load_dwordx4 v[100:103], v0, s[6:7] offset:1024
	global_load_dwordx4 v[104:107], v0, s[6:7] offset:2048
	global_load_dwordx4 v[108:111], v0, s[6:7] offset:3072
	v_mov_b32_e32 v112, 0x3727c5ac
	s_add_i32 s12, s2, s3
	s_cmp_lt_i32 s12, 0x10000
	s_cselect_b32 s13, s12, s2
	s_lshl_b32 s4, s2, 12
	s_add_u32 s4, s24, s4
	s_addc_u32 s5, s25, 0
	s_lshl_b32 s6, s13, 12
	s_add_u32 s6, s24, s6
	s_addc_u32 s7, s25, 0
	global_load_dwordx4 v[48:51], v0, s[4:5] offset:0
	global_load_dwordx4 v[52:55], v0, s[4:5] offset:1024
	global_load_dwordx4 v[56:59], v0, s[4:5] offset:2048
	global_load_dwordx4 v[60:63], v0, s[4:5] offset:3072
	global_load_dwordx4 v[64:67], v0, s[6:7] offset:0
	global_load_dwordx4 v[68:71], v0, s[6:7] offset:1024
	global_load_dwordx4 v[72:75], v0, s[6:7] offset:2048
	global_load_dwordx4 v[76:79], v0, s[6:7] offset:3072
	s_waitcnt vmcnt(0)
	s_branch .Llnb2_enter

.Llnb2_nopf:
	v_add_f32_e32 v113, v16, v20
	v_add_f32_e32 v114, v17, v21
	v_add_f32_e32 v115, v18, v22
	v_add_f32_e32 v116, v19, v23
	v_add_f32_e32 v117, v32, v36
	v_add_f32_e32 v118, v33, v37
	v_add_f32_e32 v119, v34, v38
	v_add_f32_e32 v120, v35, v39
	v_add_f32_e32 v113, v113, v24
	v_add_f32_e32 v113, v113, v28
	v_add_f32_e32 v114, v114, v25
	v_add_f32_e32 v114, v114, v29
	v_add_f32_e32 v115, v115, v26
	v_add_f32_e32 v115, v115, v30
	v_add_f32_e32 v116, v116, v27
	v_add_f32_e32 v116, v116, v31
	v_add_f32_e32 v117, v117, v40
	v_add_f32_e32 v117, v117, v44
	v_add_f32_e32 v118, v118, v41
	v_add_f32_e32 v118, v118, v45
	v_add_f32_e32 v119, v119, v42
	v_add_f32_e32 v119, v119, v46
	v_add_f32_e32 v120, v120, v43
	v_add_f32_e32 v120, v120, v47
	v_add_f32_e32 v113, v113, v114
	v_add_f32_e32 v115, v115, v116
	v_add_f32_e32 v117, v117, v118
	v_add_f32_e32 v119, v119, v120
	v_add_f32_e32 v113, v113, v115
	v_add_f32_e32 v117, v117, v119
	s_nop 1
	v_add_f32_dpp v113, v113, v113 quad_perm:[1,0,3,2] row_mask:0xf bank_mask:0xf
	v_add_f32_dpp v117, v117, v117 quad_perm:[1,0,3,2] row_mask:0xf bank_mask:0xf
	s_nop 1
	v_add_f32_dpp v113, v113, v113 quad_perm:[2,3,0,1] row_mask:0xf bank_mask:0xf
	v_add_f32_dpp v117, v117, v117 quad_perm:[2,3,0,1] row_mask:0xf bank_mask:0xf
	s_nop 1
	v_add_f32_dpp v113, v113, v113 row_half_mirror row_mask:0xf bank_mask:0xf
	v_add_f32_dpp v117, v117, v117 row_half_mirror row_mask:0xf bank_mask:0xf
	s_nop 1
	v_add_f32_dpp v113, v113, v113 row_mirror row_mask:0xf bank_mask:0xf
	v_add_f32_dpp v117, v117, v117 row_mirror row_mask:0xf bank_mask:0xf
	s_nop 1
	v_readlane_b32 s4, v113, 0
	v_readlane_b32 s5, v113, 16
	v_readlane_b32 s6, v113, 32
	v_readlane_b32 s7, v113, 48
	v_readlane_b32 s12, v117, 0
	v_readlane_b32 s13, v117, 16
	v_readlane_b32 s0, v117, 32
	v_readlane_b32 s1, v117, 48
	s_nop 1
	v_mov_b32_e32 v113, s4
	v_mov_b32_e32 v117, s12
	v_add_f32_e32 v113, s5, v113
	v_add_f32_e32 v117, s13, v117
	v_add_f32_e32 v113, s6, v113
	v_add_f32_e32 v117, s0, v117
	v_add_f32_e32 v113, s7, v113
	v_add_f32_e32 v117, s1, v117
	v_fmamk_f32 v16, v113, 0xba800000, v16
	v_fmamk_f32 v17, v113, 0xba800000, v17
	v_fmamk_f32 v18, v113, 0xba800000, v18
	v_fmamk_f32 v19, v113, 0xba800000, v19
	v_fmamk_f32 v20, v113, 0xba800000, v20
	v_fmamk_f32 v21, v113, 0xba800000, v21
	v_fmamk_f32 v22, v113, 0xba800000, v22
	v_fmamk_f32 v23, v113, 0xba800000, v23
	v_fmamk_f32 v24, v113, 0xba800000, v24
	v_fmamk_f32 v25, v113, 0xba800000, v25
	v_fmamk_f32 v26, v113, 0xba800000, v26
	v_fmamk_f32 v27, v113, 0xba800000, v27
	v_fmamk_f32 v28, v113, 0xba800000, v28
	v_fmamk_f32 v29, v113, 0xba800000, v29
	v_fmamk_f32 v30, v113, 0xba800000, v30
	v_fmamk_f32 v31, v113, 0xba800000, v31
	v_fmamk_f32 v32, v117, 0xba800000, v32
	v_fmamk_f32 v33, v117, 0xba800000, v33
	v_fmamk_f32 v34, v117, 0xba800000, v34
	v_fmamk_f32 v35, v117, 0xba800000, v35
	v_fmamk_f32 v36, v117, 0xba800000, v36
	v_fmamk_f32 v37, v117, 0xba800000, v37
	v_fmamk_f32 v38, v117, 0xba800000, v38
	v_fmamk_f32 v39, v117, 0xba800000, v39
	v_fmamk_f32 v40, v117, 0xba800000, v40
	v_fmamk_f32 v41, v117, 0xba800000, v41
	v_fmamk_f32 v42, v117, 0xba800000, v42
	v_fmamk_f32 v43, v117, 0xba800000, v43
	v_fmamk_f32 v44, v117, 0xba800000, v44
	v_fmamk_f32 v45, v117, 0xba800000, v45
	v_fmamk_f32 v46, v117, 0xba800000, v46
	v_fmamk_f32 v47, v117, 0xba800000, v47
	v_mul_f32_e32 v113, v16, v16
	v_mul_f32_e32 v114, v17, v17
	v_mul_f32_e32 v115, v18, v18
	v_mul_f32_e32 v116, v19, v19
	v_mul_f32_e32 v117, v32, v32
	v_mul_f32_e32 v118, v33, v33
	v_mul_f32_e32 v119, v34, v34
	v_mul_f32_e32 v120, v35, v35
	v_fmac_f32_e32 v113, v20, v20
	v_fmac_f32_e32 v113, v24, v24
	v_fmac_f32_e32 v113, v28, v28
	v_fmac_f32_e32 v114, v21, v21
	v_fmac_f32_e32 v114, v25, v25
	v_fmac_f32_e32 v114, v29, v29
	v_fmac_f32_e32 v115, v22, v22
	v_fmac_f32_e32 v115, v26, v26
	v_fmac_f32_e32 v115, v30, v30
	v_fmac_f32_e32 v116, v23, v23
	v_fmac_f32_e32 v116, v27, v27
	v_fmac_f32_e32 v116, v31, v31
	v_fmac_f32_e32 v117, v36, v36
	v_fmac_f32_e32 v117, v40, v40
	v_fmac_f32_e32 v117, v44, v44
	v_fmac_f32_e32 v118, v37, v37
	v_fmac_f32_e32 v118, v41, v41
	v_fmac_f32_e32 v118, v45, v45
	v_fmac_f32_e32 v119, v38, v38
	v_fmac_f32_e32 v119, v42, v42
	v_fmac_f32_e32 v119, v46, v46
	v_fmac_f32_e32 v120, v39, v39
	v_fmac_f32_e32 v120, v43, v43
	v_fmac_f32_e32 v120, v47, v47
	v_add_f32_e32 v113, v113, v114
	v_add_f32_e32 v115, v115, v116
	v_add_f32_e32 v117, v117, v118
	v_add_f32_e32 v119, v119, v120
	v_add_f32_e32 v113, v113, v115
	v_add_f32_e32 v117, v117, v119
	s_nop 1
	v_add_f32_dpp v113, v113, v113 quad_perm:[1,0,3,2] row_mask:0xf bank_mask:0xf
	v_add_f32_dpp v117, v117, v117 quad_perm:[1,0,3,2] row_mask:0xf bank_mask:0xf
	s_nop 1
	v_add_f32_dpp v113, v113, v113 quad_perm:[2,3,0,1] row_mask:0xf bank_mask:0xf
	v_add_f32_dpp v117, v117, v117 quad_perm:[2,3,0,1] row_mask:0xf bank_mask:0xf
	s_nop 1
	v_add_f32_dpp v113, v113, v113 row_half_mirror row_mask:0xf bank_mask:0xf
	v_add_f32_dpp v117, v117, v117 row_half_mirror row_mask:0xf bank_mask:0xf
	s_nop 1
	v_add_f32_dpp v113, v113, v113 row_mirror row_mask:0xf bank_mask:0xf
	v_add_f32_dpp v117, v117, v117 row_mirror row_mask:0xf bank_mask:0xf
	s_nop 1
	v_readlane_b32 s4, v113, 0
	v_readlane_b32 s5, v113, 16
	v_readlane_b32 s6, v113, 32
	v_readlane_b32 s7, v113, 48
	v_readlane_b32 s12, v117, 0
	v_readlane_b32 s13, v117, 16
	v_readlane_b32 s0, v117, 32
	v_readlane_b32 s1, v117, 48
	s_nop 1
	v_mov_b32_e32 v113, s4
	v_mov_b32_e32 v117, s12
	v_add_f32_e32 v113, s5, v113
	v_add_f32_e32 v117, s13, v117
	v_add_f32_e32 v113, s6, v113
	v_add_f32_e32 v117, s0, v117
	v_add_f32_e32 v113, s7, v113
	v_add_f32_e32 v117, s1, v117
	v_fmamk_f32 v113, v113, 0x3a800000, v112
	v_fmamk_f32 v117, v117, 0x3a800000, v112
	v_rsq_f32_e32 v113, v113
	v_rsq_f32_e32 v117, v117
	s_nop 0
	v_mul_f32_e32 v16, v16, v113
	v_mul_f32_e32 v17, v17, v113
	v_mul_f32_e32 v18, v18, v113
	v_mul_f32_e32 v19, v19, v113
	v_mul_f32_e32 v20, v20, v113
	v_mul_f32_e32 v21, v21, v113
	v_mul_f32_e32 v22, v22, v113
	v_mul_f32_e32 v23, v23, v113
	v_mul_f32_e32 v24, v24, v113
	v_mul_f32_e32 v25, v25, v113
	v_mul_f32_e32 v26, v26, v113
	v_mul_f32_e32 v27, v27, v113
	v_mul_f32_e32 v28, v28, v113
	v_mul_f32_e32 v29, v29, v113
	v_mul_f32_e32 v30, v30, v113
	v_mul_f32_e32 v31, v31, v113
	v_fma_f32 v16, v16, v80, v96
	v_fma_f32 v17, v17, v81, v97
	v_fma_f32 v18, v18, v82, v98
	v_fma_f32 v19, v19, v83, v99
	v_fma_f32 v20, v20, v84, v100
	v_fma_f32 v21, v21, v85, v101
	v_fma_f32 v22, v22, v86, v102
	v_fma_f32 v23, v23, v87, v103
	v_fma_f32 v24, v24, v88, v104
	v_fma_f32 v25, v25, v89, v105
	v_fma_f32 v26, v26, v90, v106
	v_fma_f32 v27, v27, v91, v107
	v_fma_f32 v28, v28, v92, v108
	v_fma_f32 v29, v29, v93, v109
	v_fma_f32 v30, v30, v94, v110
	v_fma_f32 v31, v31, v95, v111
	v_mul_f32_e32 v32, v32, v117
	v_mul_f32_e32 v33, v33, v117
	v_mul_f32_e32 v34, v34, v117
	v_mul_f32_e32 v35, v35, v117
	v_mul_f32_e32 v36, v36, v117
	v_mul_f32_e32 v37, v37, v117
	v_mul_f32_e32 v38, v38, v117
	v_mul_f32_e32 v39, v39, v117
	v_mul_f32_e32 v40, v40, v117
	v_mul_f32_e32 v41, v41, v117
	v_mul_f32_e32 v42, v42, v117
	v_mul_f32_e32 v43, v43, v117
	v_mul_f32_e32 v44, v44, v117
	v_mul_f32_e32 v45, v45, v117
	v_mul_f32_e32 v46, v46, v117
	v_mul_f32_e32 v47, v47, v117
	v_fma_f32 v32, v32, v80, v96
	v_fma_f32 v33, v33, v81, v97
	v_fma_f32 v34, v34, v82, v98
	v_fma_f32 v35, v35, v83, v99
	v_fma_f32 v36, v36, v84, v100
	v_fma_f32 v37, v37, v85, v101
	v_fma_f32 v38, v38, v86, v102
	v_fma_f32 v39, v39, v87, v103
	v_fma_f32 v40, v40, v88, v104
	v_fma_f32 v41, v41, v89, v105
	v_fma_f32 v42, v42, v90, v106
	v_fma_f32 v43, v43, v91, v107
	v_fma_f32 v44, v44, v92, v108
	v_fma_f32 v45, v45, v93, v109
	v_fma_f32 v46, v46, v94, v110
	v_fma_f32 v47, v47, v95, v111
	s_lshl_b32 s4, s8, 12
	s_add_u32 s4, s24, s4
	s_addc_u32 s5, s25, 0
	global_store_dwordx4 v0, v[16:19], s[4:5] offset:0
	global_store_dwordx4 v0, v[20:23], s[4:5] offset:1024
	global_store_dwordx4 v0, v[24:27], s[4:5] offset:2048
	global_store_dwordx4 v0, v[28:31], s[4:5] offset:3072
	s_cmp_ge_i32 s9, 0x10000
	s_cbranch_scc1 .Llnb2_st1
	s_lshl_b32 s6, s9, 12
	s_add_u32 s6, s24, s6
	s_addc_u32 s7, s25, 0
	global_store_dwordx4 v0, v[32:35], s[6:7] offset:0
	global_store_dwordx4 v0, v[36:39], s[6:7] offset:1024
	global_store_dwordx4 v0, v[40:43], s[6:7] offset:2048
	global_store_dwordx4 v0, v[44:47], s[6:7] offset:3072

.Llnb2_done:
.LBB0_1779:
	s_or_b64 exec, exec, s[10:11]
	s_cmp_lt_i32 s29, 22
	s_cbranch_scc1 .LBB0_1833
	s_waitcnt vmcnt(0)
	s_waitcnt vmcnt(0) lgkmcnt(0)
	s_barrier
	s_mov_b64 s[2:3], exec
	v_readlane_b32 s0, v254, 1
	v_readlane_b32 s1, v254, 2
	s_and_b64 s[0:1], s[2:3], s[0:1]
	s_mov_b64 exec, s[0:1]
	s_cbranch_execz .LBB0_1832
	s_add_i32 s0, 0, 0x20400
	v_mov_b32_e32 v0, s0
	s_waitcnt vmcnt(0) expcnt(0) lgkmcnt(0)
	ds_read_b32 v2, v0
	s_add_i32 s0, 0, 0x20404
	v_mov_b32_e32 v0, s0
	ds_read_b32 v0, v0
	s_waitcnt lgkmcnt(1)
	v_cmp_ne_u32_e32 vcc, 0, v2
	s_cbranch_vccnz .LBB0_1796
	v_readlane_b32 s0, v254, 0
	s_mul_i32 s48, s31, s0
	s_add_u32 s0, s26, 0x3300200
	s_addc_u32 s1, s27, 0
	s_add_u32 s4, s26, 0x3300400
	s_addc_u32 s5, s27, 0
	s_add_u32 s6, s26, 0x3300500
	s_addc_u32 s7, s27, 0
	s_add_u32 s8, s26, 0x3300600
	s_addc_u32 s9, s27, 0
	s_add_u32 s10, s26, 0x3300700
	s_addc_u32 s11, s27, 0
	s_add_u32 s12, s26, 0x3300800
	s_addc_u32 s13, s27, 0
	s_add_u32 s14, s26, 0x3300900
	s_addc_u32 s15, s27, 0
	s_add_u32 s16, s26, 0x3300a00
	s_addc_u32 s17, s27, 0
	s_add_u32 s18, s26, 0x3300b00
	s_addc_u32 s19, s27, 0
	s_add_u32 s20, s26, 0x3300c00
	s_addc_u32 s21, s27, 0
	s_add_u32 s24, s26, 0x3300d00
	s_addc_u32 s25, s27, 0
	s_add_u32 s28, s26, 0x3300e00
	s_addc_u32 s29, s27, 0
	s_mul_i32 s48, s48, s30
	s_add_u32 s30, s26, 0x3300f00
	s_addc_u32 s31, s27, 0
	s_add_u32 s34, s26, 0x3301000
	s_addc_u32 s35, s27, 0
	s_add_u32 s36, s26, 0x3301100
	s_addc_u32 s37, s27, 0
	s_add_u32 s38, s26, 0x3301200
	s_addc_u32 s39, s27, 0
	s_add_u32 s40, s26, 0x3301300
	s_addc_u32 s41, s27, 0
	s_mov_b32 s49, 1
	v_mov_b32_e32 v16, 0
	s_branch .LBB0_1784
